# v3 + lever 9 (loop-edge): SALU counter/pointer block of the six K=2048 GEMM K-loops hoisted above the loop-back s_barrier (branch stays after it)
# speedup vs baseline: 1.0003x; 1.0003x over previous
.LBB0_142:
	ds_read_b128 v[156:159], v171
	ds_read_b128 v[160:163], v171 offset:1024
	ds_read_b128 v[174:177], v171 offset:2048
	ds_read_b128 v[178:181], v171 offset:3072
	ds_read_b128 v[182:185], v172
	ds_read_b128 v[186:189], v172 offset:1024
	ds_read_b128 v[190:193], v172 offset:2048
	ds_read_b128 v[194:197], v172 offset:3072
	s_add_u32 s0, s8, 0xfff80080
	s_addc_u32 s1, s9, -1
	s_cmp_eq_u32 s37, 28
	s_cselect_b32 s3, s5, s1
	s_cselect_b32 s2, s14, s0
	s_cselect_b32 s1, s25, s36
	s_cselect_b32 s0, s27, s33
	v_lshl_add_u64 v[164:165], s[8:9], 0, v[148:149]
	s_add_i32 m0, s35, 0xc000
	ds_read_b128 v[198:201], v173
	ds_read_b128 v[202:205], v173 offset:1024
	ds_read_b128 v[206:209], v173 offset:2048
	ds_read_b128 v[210:213], v173 offset:3072
	ds_read_b128 v[214:217], v173 offset:4096
	ds_read_b128 v[218:221], v173 offset:5120
	ds_read_b128 v[222:225], v173 offset:6144
	ds_read_b128 v[226:229], v173 offset:7168
	global_load_lds_dwordx4 v[164:165], off
	v_lshl_add_u64 v[164:165], s[8:9], 0, v[150:151]
	s_add_i32 m0, s35, 0xe000
	s_nop 0
	global_load_lds_dwordx4 v[164:165], off
	s_waitcnt vmcnt(8)
	s_waitcnt lgkmcnt(0)
	s_barrier
	s_setprio 1
	s_waitcnt lgkmcnt(0)
	v_mfma_f32_16x16x32_bf16 v[126:129], v[156:159], v[198:201], v[126:129]
	v_mfma_f32_16x16x32_bf16 v[122:125], v[174:177], v[198:201], v[122:125]
	v_mfma_f32_16x16x32_bf16 v[118:121], v[156:159], v[206:209], v[118:121]
	v_mfma_f32_16x16x32_bf16 v[110:113], v[174:177], v[206:209], v[110:113]
	v_mfma_f32_16x16x32_bf16 v[102:105], v[156:159], v[214:217], v[102:105]
	v_mfma_f32_16x16x32_bf16 v[94:97], v[174:177], v[214:217], v[94:97]
	v_mfma_f32_16x16x32_bf16 v[86:89], v[156:159], v[222:225], v[86:89]
	v_mfma_f32_16x16x32_bf16 v[78:81], v[174:177], v[222:225], v[78:81]
	v_mfma_f32_16x16x32_bf16 v[126:129], v[160:163], v[202:205], v[126:129]
	v_mfma_f32_16x16x32_bf16 v[122:125], v[178:181], v[202:205], v[122:125]
	v_mfma_f32_16x16x32_bf16 v[118:121], v[160:163], v[210:213], v[118:121]
	v_mfma_f32_16x16x32_bf16 v[110:113], v[178:181], v[210:213], v[110:113]
	v_mfma_f32_16x16x32_bf16 v[102:105], v[160:163], v[218:221], v[102:105]
	v_mfma_f32_16x16x32_bf16 v[94:97], v[178:181], v[218:221], v[94:97]
	v_mfma_f32_16x16x32_bf16 v[86:89], v[160:163], v[226:229], v[86:89]
	v_mfma_f32_16x16x32_bf16 v[78:81], v[178:181], v[226:229], v[78:81]
	s_setprio 0
	s_setprio 1
	v_mfma_f32_16x16x32_bf16 v[114:117], v[182:185], v[198:201], v[114:117]
	v_mfma_f32_16x16x32_bf16 v[106:109], v[190:193], v[198:201], v[106:109]
	v_mfma_f32_16x16x32_bf16 v[98:101], v[182:185], v[206:209], v[98:101]
	v_mfma_f32_16x16x32_bf16 v[90:93], v[190:193], v[206:209], v[90:93]
	v_mfma_f32_16x16x32_bf16 v[82:85], v[182:185], v[214:217], v[82:85]
	v_mfma_f32_16x16x32_bf16 v[74:77], v[190:193], v[214:217], v[74:77]
	v_mfma_f32_16x16x32_bf16 v[70:73], v[182:185], v[222:225], v[70:73]
	v_mfma_f32_16x16x32_bf16 v[66:69], v[190:193], v[222:225], v[66:69]
	v_mfma_f32_16x16x32_bf16 v[114:117], v[186:189], v[202:205], v[114:117]
	v_mfma_f32_16x16x32_bf16 v[106:109], v[194:197], v[202:205], v[106:109]
	v_mfma_f32_16x16x32_bf16 v[98:101], v[186:189], v[210:213], v[98:101]
	v_mfma_f32_16x16x32_bf16 v[90:93], v[194:197], v[210:213], v[90:93]
	v_mfma_f32_16x16x32_bf16 v[82:85], v[186:189], v[218:221], v[82:85]
	v_mfma_f32_16x16x32_bf16 v[74:77], v[194:197], v[218:221], v[74:77]
	v_mfma_f32_16x16x32_bf16 v[70:73], v[186:189], v[226:229], v[70:73]
	v_mfma_f32_16x16x32_bf16 v[66:69], v[194:197], v[226:229], v[66:69]
	s_setprio 0
	s_barrier
	s_add_i32 s38, s55, s43
	v_lshl_add_u64 v[164:165], s[0:1], 0, v[136:137]
	s_mov_b32 m0, s38
	ds_read_b128 v[198:201], v173 offset:16384
	ds_read_b128 v[202:205], v173 offset:17408
	ds_read_b128 v[206:209], v173 offset:18432
	ds_read_b128 v[210:213], v173 offset:19456
	ds_read_b128 v[214:217], v173 offset:20480
	ds_read_b128 v[218:221], v173 offset:21504
	ds_read_b128 v[222:225], v173 offset:22528
	ds_read_b128 v[226:229], v173 offset:23552
	global_load_lds_dwordx4 v[164:165], off
	s_add_i32 m0, s38, 0x2000
	s_add_u32 s38, s0, 0x80000
	v_lshl_add_u64 v[230:231], s[0:1], 0, v[142:143]
	s_addc_u32 s39, s1, 0
	s_add_i32 s61, s56, s43
	global_load_lds_dwordx4 v[230:231], off
	v_lshl_add_u64 v[232:233], s[38:39], 0, v[136:137]
	s_mov_b32 m0, s61
	v_lshl_add_u64 v[234:235], s[2:3], 0, v[140:141]
	global_load_lds_dwordx4 v[232:233], off
	v_lshl_add_u64 v[232:233], s[38:39], 0, v[142:143]
	s_add_i32 m0, s61, 0x2000
	s_nop 0
	global_load_lds_dwordx4 v[232:233], off
	v_lshl_add_u64 v[232:233], s[2:3], 0, v[134:135]
	s_mov_b32 m0, s35
	s_nop 0
	global_load_lds_dwordx4 v[232:233], off
	s_mov_b32 m0, s44
	s_nop 0
	global_load_lds_dwordx4 v[234:235], off
	s_waitcnt vmcnt(8)
	s_waitcnt lgkmcnt(0)
	s_barrier
	s_setprio 1
	s_waitcnt lgkmcnt(0)
	v_mfma_f32_16x16x32_bf16 v[62:65], v[156:159], v[198:201], v[62:65]
	v_mfma_f32_16x16x32_bf16 v[58:61], v[174:177], v[198:201], v[58:61]
	v_mfma_f32_16x16x32_bf16 v[54:57], v[156:159], v[206:209], v[54:57]
	v_mfma_f32_16x16x32_bf16 v[46:49], v[174:177], v[206:209], v[46:49]
	v_mfma_f32_16x16x32_bf16 v[38:41], v[156:159], v[214:217], v[38:41]
	v_mfma_f32_16x16x32_bf16 v[30:33], v[174:177], v[214:217], v[30:33]
	v_mfma_f32_16x16x32_bf16 v[22:25], v[156:159], v[222:225], v[22:25]
	v_mfma_f32_16x16x32_bf16 v[14:17], v[174:177], v[222:225], v[14:17]
	v_mfma_f32_16x16x32_bf16 v[62:65], v[160:163], v[202:205], v[62:65]
	v_mfma_f32_16x16x32_bf16 v[58:61], v[178:181], v[202:205], v[58:61]
	v_mfma_f32_16x16x32_bf16 v[54:57], v[160:163], v[210:213], v[54:57]
	v_mfma_f32_16x16x32_bf16 v[46:49], v[178:181], v[210:213], v[46:49]
	v_mfma_f32_16x16x32_bf16 v[38:41], v[160:163], v[218:221], v[38:41]
	v_mfma_f32_16x16x32_bf16 v[30:33], v[178:181], v[218:221], v[30:33]
	v_mfma_f32_16x16x32_bf16 v[22:25], v[160:163], v[226:229], v[22:25]
	v_mfma_f32_16x16x32_bf16 v[14:17], v[178:181], v[226:229], v[14:17]
	s_setprio 0
	s_setprio 1
	v_mfma_f32_16x16x32_bf16 v[50:53], v[182:185], v[198:201], v[50:53]
	v_mfma_f32_16x16x32_bf16 v[42:45], v[190:193], v[198:201], v[42:45]
	v_mfma_f32_16x16x32_bf16 v[34:37], v[182:185], v[206:209], v[34:37]
	v_mfma_f32_16x16x32_bf16 v[26:29], v[190:193], v[206:209], v[26:29]
	v_mfma_f32_16x16x32_bf16 v[18:21], v[182:185], v[214:217], v[18:21]
	v_mfma_f32_16x16x32_bf16 v[10:13], v[190:193], v[214:217], v[10:13]
	v_mfma_f32_16x16x32_bf16 v[6:9], v[182:185], v[222:225], v[6:9]
	v_mfma_f32_16x16x32_bf16 v[2:5], v[190:193], v[222:225], v[2:5]
	v_mfma_f32_16x16x32_bf16 v[50:53], v[186:189], v[202:205], v[50:53]
	v_mfma_f32_16x16x32_bf16 v[42:45], v[194:197], v[202:205], v[42:45]
	v_mfma_f32_16x16x32_bf16 v[34:37], v[186:189], v[210:213], v[34:37]
	v_mfma_f32_16x16x32_bf16 v[26:29], v[194:197], v[210:213], v[26:29]
	v_mfma_f32_16x16x32_bf16 v[18:21], v[186:189], v[218:221], v[18:21]
	v_mfma_f32_16x16x32_bf16 v[10:13], v[194:197], v[218:221], v[10:13]
	v_mfma_f32_16x16x32_bf16 v[6:9], v[186:189], v[226:229], v[6:9]
	v_mfma_f32_16x16x32_bf16 v[2:5], v[194:197], v[226:229], v[2:5]
	s_setprio 0
	s_barrier
	s_add_i32 s38, 0, 0x18000
	v_add_u32_e32 v144, s38, v170
	s_add_i32 s39, 0, 0x1c000
	ds_read_b128 v[156:159], v144
	ds_read_b128 v[160:163], v144 offset:1024
	ds_read_b128 v[174:177], v144 offset:2048
	ds_read_b128 v[178:181], v144 offset:3072
	v_add_u32_e32 v144, s39, v170
	ds_read_b128 v[182:185], v144
	ds_read_b128 v[186:189], v144 offset:1024
	ds_read_b128 v[190:193], v144 offset:2048
	ds_read_b128 v[194:197], v144 offset:3072
	s_add_u32 s2, s2, 0x80000
	s_addc_u32 s3, s3, 0
	s_mov_b32 m0, s45
	v_lshl_add_u64 v[236:237], s[2:3], 0, v[134:135]
	ds_read_b128 v[198:201], v173 offset:32768
	ds_read_b128 v[202:205], v173 offset:33792
	ds_read_b128 v[206:209], v173 offset:34816
	ds_read_b128 v[210:213], v173 offset:35840
	ds_read_b128 v[214:217], v173 offset:36864
	ds_read_b128 v[218:221], v173 offset:37888
	ds_read_b128 v[222:225], v173 offset:38912
	ds_read_b128 v[226:229], v173 offset:39936
	global_load_lds_dwordx4 v[236:237], off
	v_lshl_add_u64 v[236:237], s[2:3], 0, v[140:141]
	s_mov_b32 m0, s46
	s_nop 0
	global_load_lds_dwordx4 v[236:237], off
	s_waitcnt vmcnt(8)
	s_waitcnt lgkmcnt(0)
	s_barrier
	s_setprio 1
	s_waitcnt lgkmcnt(0)
	v_mfma_f32_16x16x32_bf16 v[126:129], v[156:159], v[198:201], v[126:129]
	v_mfma_f32_16x16x32_bf16 v[122:125], v[174:177], v[198:201], v[122:125]
	v_mfma_f32_16x16x32_bf16 v[118:121], v[156:159], v[206:209], v[118:121]
	v_mfma_f32_16x16x32_bf16 v[110:113], v[174:177], v[206:209], v[110:113]
	v_mfma_f32_16x16x32_bf16 v[102:105], v[156:159], v[214:217], v[102:105]
	v_mfma_f32_16x16x32_bf16 v[94:97], v[174:177], v[214:217], v[94:97]
	v_mfma_f32_16x16x32_bf16 v[86:89], v[156:159], v[222:225], v[86:89]
	v_mfma_f32_16x16x32_bf16 v[78:81], v[174:177], v[222:225], v[78:81]
	v_mfma_f32_16x16x32_bf16 v[126:129], v[160:163], v[202:205], v[126:129]
	v_mfma_f32_16x16x32_bf16 v[122:125], v[178:181], v[202:205], v[122:125]
	v_mfma_f32_16x16x32_bf16 v[118:121], v[160:163], v[210:213], v[118:121]
	v_mfma_f32_16x16x32_bf16 v[110:113], v[178:181], v[210:213], v[110:113]
	v_mfma_f32_16x16x32_bf16 v[102:105], v[160:163], v[218:221], v[102:105]
	v_mfma_f32_16x16x32_bf16 v[94:97], v[178:181], v[218:221], v[94:97]
	v_mfma_f32_16x16x32_bf16 v[86:89], v[160:163], v[226:229], v[86:89]
	v_mfma_f32_16x16x32_bf16 v[78:81], v[178:181], v[226:229], v[78:81]
	s_setprio 0
	s_setprio 1
	v_mfma_f32_16x16x32_bf16 v[114:117], v[182:185], v[198:201], v[114:117]
	v_mfma_f32_16x16x32_bf16 v[106:109], v[190:193], v[198:201], v[106:109]
	v_mfma_f32_16x16x32_bf16 v[98:101], v[182:185], v[206:209], v[98:101]
	v_mfma_f32_16x16x32_bf16 v[90:93], v[190:193], v[206:209], v[90:93]
	v_mfma_f32_16x16x32_bf16 v[82:85], v[182:185], v[214:217], v[82:85]
	v_mfma_f32_16x16x32_bf16 v[74:77], v[190:193], v[214:217], v[74:77]
	v_mfma_f32_16x16x32_bf16 v[70:73], v[182:185], v[222:225], v[70:73]
	v_mfma_f32_16x16x32_bf16 v[66:69], v[190:193], v[222:225], v[66:69]
	v_mfma_f32_16x16x32_bf16 v[114:117], v[186:189], v[202:205], v[114:117]
	v_mfma_f32_16x16x32_bf16 v[106:109], v[194:197], v[202:205], v[106:109]
	v_mfma_f32_16x16x32_bf16 v[98:101], v[186:189], v[210:213], v[98:101]
	v_mfma_f32_16x16x32_bf16 v[90:93], v[194:197], v[210:213], v[90:93]
	v_mfma_f32_16x16x32_bf16 v[82:85], v[186:189], v[218:221], v[82:85]
	v_mfma_f32_16x16x32_bf16 v[74:77], v[194:197], v[218:221], v[74:77]
	v_mfma_f32_16x16x32_bf16 v[70:73], v[186:189], v[226:229], v[70:73]
	v_mfma_f32_16x16x32_bf16 v[66:69], v[194:197], v[226:229], v[66:69]
	s_setprio 0
	s_barrier
	s_add_i32 s2, s38, s43
	v_lshl_add_u64 v[164:165], v[164:165], 0, s[18:19]
	s_mov_b32 m0, s2
	ds_read_b128 v[198:201], v173 offset:49152
	ds_read_b128 v[202:205], v173 offset:50176
	ds_read_b128 v[206:209], v173 offset:51200
	ds_read_b128 v[210:213], v173 offset:52224
	ds_read_b128 v[214:217], v173 offset:53248
	ds_read_b128 v[218:221], v173 offset:54272
	ds_read_b128 v[222:225], v173 offset:55296
	ds_read_b128 v[226:229], v173 offset:56320
	global_load_lds_dwordx4 v[164:165], off
	s_add_i32 m0, s2, 0x2000
	s_add_u32 s0, s0, 0x80080
	v_lshl_add_u64 v[164:165], v[230:231], 0, s[18:19]
	s_addc_u32 s1, s1, 0
	s_add_i32 s2, s39, s43
	global_load_lds_dwordx4 v[164:165], off
	v_lshl_add_u64 v[164:165], s[0:1], 0, v[136:137]
	s_mov_b32 m0, s2
	s_nop 0
	global_load_lds_dwordx4 v[164:165], off
	v_lshl_add_u64 v[164:165], s[0:1], 0, v[142:143]
	s_add_i32 m0, s2, 0x2000
	s_nop 0
	global_load_lds_dwordx4 v[164:165], off
	v_lshl_add_u64 v[164:165], v[232:233], 0, s[18:19]
	s_mov_b32 m0, s48
	s_nop 0
	global_load_lds_dwordx4 v[164:165], off
	v_lshl_add_u64 v[164:165], v[234:235], 0, s[18:19]
	s_mov_b32 m0, s49
	s_nop 0
	global_load_lds_dwordx4 v[164:165], off
	s_waitcnt vmcnt(8)
	s_waitcnt lgkmcnt(0)
	s_barrier
	s_setprio 1
	s_waitcnt lgkmcnt(0)
	v_mfma_f32_16x16x32_bf16 v[62:65], v[156:159], v[198:201], v[62:65]
	v_mfma_f32_16x16x32_bf16 v[58:61], v[174:177], v[198:201], v[58:61]
	v_mfma_f32_16x16x32_bf16 v[54:57], v[156:159], v[206:209], v[54:57]
	v_mfma_f32_16x16x32_bf16 v[46:49], v[174:177], v[206:209], v[46:49]
	v_mfma_f32_16x16x32_bf16 v[38:41], v[156:159], v[214:217], v[38:41]
	v_mfma_f32_16x16x32_bf16 v[30:33], v[174:177], v[214:217], v[30:33]
	v_mfma_f32_16x16x32_bf16 v[22:25], v[156:159], v[222:225], v[22:25]
	v_mfma_f32_16x16x32_bf16 v[14:17], v[174:177], v[222:225], v[14:17]
	v_mfma_f32_16x16x32_bf16 v[62:65], v[160:163], v[202:205], v[62:65]
	v_mfma_f32_16x16x32_bf16 v[58:61], v[178:181], v[202:205], v[58:61]
	v_mfma_f32_16x16x32_bf16 v[54:57], v[160:163], v[210:213], v[54:57]
	v_mfma_f32_16x16x32_bf16 v[46:49], v[178:181], v[210:213], v[46:49]
	v_mfma_f32_16x16x32_bf16 v[38:41], v[160:163], v[218:221], v[38:41]
	v_mfma_f32_16x16x32_bf16 v[30:33], v[178:181], v[218:221], v[30:33]
	v_mfma_f32_16x16x32_bf16 v[22:25], v[160:163], v[226:229], v[22:25]
	v_mfma_f32_16x16x32_bf16 v[14:17], v[178:181], v[226:229], v[14:17]
	s_setprio 0
	s_setprio 1
	v_mfma_f32_16x16x32_bf16 v[50:53], v[182:185], v[198:201], v[50:53]
	v_mfma_f32_16x16x32_bf16 v[42:45], v[190:193], v[198:201], v[42:45]
	v_mfma_f32_16x16x32_bf16 v[34:37], v[182:185], v[206:209], v[34:37]
	v_mfma_f32_16x16x32_bf16 v[26:29], v[190:193], v[206:209], v[26:29]
	v_mfma_f32_16x16x32_bf16 v[18:21], v[182:185], v[214:217], v[18:21]
	v_mfma_f32_16x16x32_bf16 v[10:13], v[190:193], v[214:217], v[10:13]
	v_mfma_f32_16x16x32_bf16 v[6:9], v[182:185], v[222:225], v[6:9]
	v_mfma_f32_16x16x32_bf16 v[2:5], v[190:193], v[222:225], v[2:5]
	v_mfma_f32_16x16x32_bf16 v[50:53], v[186:189], v[202:205], v[50:53]
	v_mfma_f32_16x16x32_bf16 v[42:45], v[194:197], v[202:205], v[42:45]
	v_mfma_f32_16x16x32_bf16 v[34:37], v[186:189], v[210:213], v[34:37]
	v_mfma_f32_16x16x32_bf16 v[26:29], v[194:197], v[210:213], v[26:29]
	v_mfma_f32_16x16x32_bf16 v[18:21], v[186:189], v[218:221], v[18:21]
	v_mfma_f32_16x16x32_bf16 v[10:13], v[194:197], v[218:221], v[10:13]
	v_mfma_f32_16x16x32_bf16 v[6:9], v[186:189], v[226:229], v[6:9]
	v_mfma_f32_16x16x32_bf16 v[2:5], v[194:197], v[226:229], v[2:5]
	s_setprio 0
	s_add_i32 s37, s37, 2
	s_add_u32 s8, s8, 0x100
	s_addc_u32 s9, s9, 0
	s_add_u32 s33, s33, 0x100
	s_addc_u32 s36, s36, 0
	s_cmp_gt_u32 s37, 29
	s_barrier
	s_cbranch_scc0 .LBB0_142
	s_and_b64 vcc, exec, s[20:21]
	s_cbranch_vccz .LBB0_145
	s_barrier

.LBB0_655:
	ds_read_b128 v[150:153], v158
	ds_read_b128 v[162:165], v158 offset:1024
	ds_read_b128 v[166:169], v158 offset:2048
	ds_read_b128 v[170:173], v158 offset:3072
	ds_read_b128 v[176:179], v159
	ds_read_b128 v[180:183], v159 offset:1024
	ds_read_b128 v[184:187], v159 offset:2048
	ds_read_b128 v[188:191], v159 offset:3072
	s_add_u32 s0, s30, 0xfff80080
	s_addc_u32 s1, s31, -1
	s_cmp_eq_u32 s53, 28
	s_cselect_b32 s3, s23, s1
	s_cselect_b32 s2, s49, s0
	s_cselect_b32 s1, s21, s52
	s_cselect_b32 s0, s50, s51
	v_lshl_add_u64 v[154:155], s[30:31], 0, v[142:143]
	s_add_i32 m0, s29, 0xc000
	ds_read_b128 v[192:195], v160
	ds_read_b128 v[196:199], v160 offset:1024
	ds_read_b128 v[200:203], v160 offset:2048
	ds_read_b128 v[204:207], v160 offset:3072
	ds_read_b128 v[208:211], v160 offset:4096
	ds_read_b128 v[212:215], v160 offset:5120
	ds_read_b128 v[216:219], v160 offset:6144
	ds_read_b128 v[220:223], v160 offset:7168
	global_load_lds_dwordx4 v[154:155], off
	v_lshl_add_u64 v[154:155], s[30:31], 0, v[144:145]
	s_add_i32 m0, s29, 0xe000
	s_nop 0
	global_load_lds_dwordx4 v[154:155], off
	s_waitcnt vmcnt(8)
	s_waitcnt lgkmcnt(0)
	s_barrier
	s_setprio 1
	s_waitcnt lgkmcnt(0)
	v_mfma_f32_16x16x32_bf16 v[126:129], v[150:153], v[192:195], v[126:129]
	v_mfma_f32_16x16x32_bf16 v[122:125], v[166:169], v[192:195], v[122:125]
	v_mfma_f32_16x16x32_bf16 v[110:113], v[150:153], v[200:203], v[110:113]
	v_mfma_f32_16x16x32_bf16 v[106:109], v[166:169], v[200:203], v[106:109]
	v_mfma_f32_16x16x32_bf16 v[94:97], v[150:153], v[208:211], v[94:97]
	v_mfma_f32_16x16x32_bf16 v[90:93], v[166:169], v[208:211], v[90:93]
	v_mfma_f32_16x16x32_bf16 v[78:81], v[150:153], v[216:219], v[78:81]
	v_mfma_f32_16x16x32_bf16 v[74:77], v[166:169], v[216:219], v[74:77]
	v_mfma_f32_16x16x32_bf16 v[126:129], v[162:165], v[196:199], v[126:129]
	v_mfma_f32_16x16x32_bf16 v[122:125], v[170:173], v[196:199], v[122:125]
	v_mfma_f32_16x16x32_bf16 v[110:113], v[162:165], v[204:207], v[110:113]
	v_mfma_f32_16x16x32_bf16 v[106:109], v[170:173], v[204:207], v[106:109]
	v_mfma_f32_16x16x32_bf16 v[94:97], v[162:165], v[212:215], v[94:97]
	v_mfma_f32_16x16x32_bf16 v[90:93], v[170:173], v[212:215], v[90:93]
	v_mfma_f32_16x16x32_bf16 v[78:81], v[162:165], v[220:223], v[78:81]
	v_mfma_f32_16x16x32_bf16 v[74:77], v[170:173], v[220:223], v[74:77]
	s_setprio 0
	s_setprio 1
	v_mfma_f32_16x16x32_bf16 v[118:121], v[176:179], v[192:195], v[118:121]
	v_mfma_f32_16x16x32_bf16 v[114:117], v[184:187], v[192:195], v[114:117]
	v_mfma_f32_16x16x32_bf16 v[102:105], v[176:179], v[200:203], v[102:105]
	v_mfma_f32_16x16x32_bf16 v[98:101], v[184:187], v[200:203], v[98:101]
	v_mfma_f32_16x16x32_bf16 v[86:89], v[176:179], v[208:211], v[86:89]
	v_mfma_f32_16x16x32_bf16 v[82:85], v[184:187], v[208:211], v[82:85]
	v_mfma_f32_16x16x32_bf16 v[70:73], v[176:179], v[216:219], v[70:73]
	v_mfma_f32_16x16x32_bf16 v[66:69], v[184:187], v[216:219], v[66:69]
	v_mfma_f32_16x16x32_bf16 v[118:121], v[180:183], v[196:199], v[118:121]
	v_mfma_f32_16x16x32_bf16 v[114:117], v[188:191], v[196:199], v[114:117]
	v_mfma_f32_16x16x32_bf16 v[102:105], v[180:183], v[204:207], v[102:105]
	v_mfma_f32_16x16x32_bf16 v[98:101], v[188:191], v[204:207], v[98:101]
	v_mfma_f32_16x16x32_bf16 v[86:89], v[180:183], v[212:215], v[86:89]
	v_mfma_f32_16x16x32_bf16 v[82:85], v[188:191], v[212:215], v[82:85]
	v_mfma_f32_16x16x32_bf16 v[70:73], v[180:183], v[220:223], v[70:73]
	v_mfma_f32_16x16x32_bf16 v[66:69], v[188:191], v[220:223], v[66:69]
	s_setprio 0
	s_barrier
	s_add_i32 s54, s46, s38
	v_lshl_add_u64 v[154:155], s[0:1], 0, v[134:135]
	s_mov_b32 m0, s54
	ds_read_b128 v[192:195], v160 offset:16384
	ds_read_b128 v[196:199], v160 offset:17408
	ds_read_b128 v[200:203], v160 offset:18432
	ds_read_b128 v[204:207], v160 offset:19456
	ds_read_b128 v[208:211], v160 offset:20480
	ds_read_b128 v[212:215], v160 offset:21504
	ds_read_b128 v[216:219], v160 offset:22528
	ds_read_b128 v[220:223], v160 offset:23552
	global_load_lds_dwordx4 v[154:155], off
	s_add_i32 m0, s54, 0x2000
	s_add_u32 s54, s0, 0x80000
	v_lshl_add_u64 v[224:225], s[0:1], 0, v[140:141]
	s_addc_u32 s55, s1, 0
	s_add_i32 s56, s47, s38
	global_load_lds_dwordx4 v[224:225], off
	v_lshl_add_u64 v[226:227], s[54:55], 0, v[134:135]
	s_mov_b32 m0, s56
	v_lshl_add_u64 v[228:229], s[2:3], 0, v[136:137]
	global_load_lds_dwordx4 v[226:227], off
	v_lshl_add_u64 v[226:227], s[54:55], 0, v[140:141]
	s_add_i32 m0, s56, 0x2000
	s_nop 0
	global_load_lds_dwordx4 v[226:227], off
	v_lshl_add_u64 v[226:227], s[2:3], 0, v[132:133]
	s_mov_b32 m0, s29
	s_nop 0
	global_load_lds_dwordx4 v[226:227], off
	s_mov_b32 m0, s39
	s_nop 0
	global_load_lds_dwordx4 v[228:229], off
	s_waitcnt vmcnt(8)
	s_waitcnt lgkmcnt(0)
	s_barrier
	s_setprio 1
	s_waitcnt lgkmcnt(0)
	v_mfma_f32_16x16x32_bf16 v[62:65], v[150:153], v[192:195], v[62:65]
	v_mfma_f32_16x16x32_bf16 v[58:61], v[166:169], v[192:195], v[58:61]
	v_mfma_f32_16x16x32_bf16 v[46:49], v[150:153], v[200:203], v[46:49]
	v_mfma_f32_16x16x32_bf16 v[42:45], v[166:169], v[200:203], v[42:45]
	v_mfma_f32_16x16x32_bf16 v[30:33], v[150:153], v[208:211], v[30:33]
	v_mfma_f32_16x16x32_bf16 v[26:29], v[166:169], v[208:211], v[26:29]
	v_mfma_f32_16x16x32_bf16 v[14:17], v[150:153], v[216:219], v[14:17]
	v_mfma_f32_16x16x32_bf16 v[10:13], v[166:169], v[216:219], v[10:13]
	v_mfma_f32_16x16x32_bf16 v[62:65], v[162:165], v[196:199], v[62:65]
	v_mfma_f32_16x16x32_bf16 v[58:61], v[170:173], v[196:199], v[58:61]
	v_mfma_f32_16x16x32_bf16 v[46:49], v[162:165], v[204:207], v[46:49]
	v_mfma_f32_16x16x32_bf16 v[42:45], v[170:173], v[204:207], v[42:45]
	v_mfma_f32_16x16x32_bf16 v[30:33], v[162:165], v[212:215], v[30:33]
	v_mfma_f32_16x16x32_bf16 v[26:29], v[170:173], v[212:215], v[26:29]
	v_mfma_f32_16x16x32_bf16 v[14:17], v[162:165], v[220:223], v[14:17]
	v_mfma_f32_16x16x32_bf16 v[10:13], v[170:173], v[220:223], v[10:13]
	s_setprio 0
	s_setprio 1
	v_mfma_f32_16x16x32_bf16 v[54:57], v[176:179], v[192:195], v[54:57]
	v_mfma_f32_16x16x32_bf16 v[50:53], v[184:187], v[192:195], v[50:53]
	v_mfma_f32_16x16x32_bf16 v[38:41], v[176:179], v[200:203], v[38:41]
	v_mfma_f32_16x16x32_bf16 v[34:37], v[184:187], v[200:203], v[34:37]
	v_mfma_f32_16x16x32_bf16 v[22:25], v[176:179], v[208:211], v[22:25]
	v_mfma_f32_16x16x32_bf16 v[18:21], v[184:187], v[208:211], v[18:21]
	v_mfma_f32_16x16x32_bf16 v[6:9], v[176:179], v[216:219], v[6:9]
	v_mfma_f32_16x16x32_bf16 v[2:5], v[184:187], v[216:219], v[2:5]
	v_mfma_f32_16x16x32_bf16 v[54:57], v[180:183], v[196:199], v[54:57]
	v_mfma_f32_16x16x32_bf16 v[50:53], v[188:191], v[196:199], v[50:53]
	v_mfma_f32_16x16x32_bf16 v[38:41], v[180:183], v[204:207], v[38:41]
	v_mfma_f32_16x16x32_bf16 v[34:37], v[188:191], v[204:207], v[34:37]
	v_mfma_f32_16x16x32_bf16 v[22:25], v[180:183], v[212:215], v[22:25]
	v_mfma_f32_16x16x32_bf16 v[18:21], v[188:191], v[212:215], v[18:21]
	v_mfma_f32_16x16x32_bf16 v[6:9], v[180:183], v[220:223], v[6:9]
	v_mfma_f32_16x16x32_bf16 v[2:5], v[188:191], v[220:223], v[2:5]
	s_setprio 0
	s_barrier
	s_add_i32 s54, 0, 0x18000
	v_add_u32_e32 v161, s54, v156
	s_add_i32 s55, 0, 0x1c000
	ds_read_b128 v[150:153], v161
	ds_read_b128 v[162:165], v161 offset:1024
	ds_read_b128 v[166:169], v161 offset:2048
	ds_read_b128 v[170:173], v161 offset:3072
	v_add_u32_e32 v161, s55, v156
	ds_read_b128 v[176:179], v161
	ds_read_b128 v[180:183], v161 offset:1024
	ds_read_b128 v[184:187], v161 offset:2048
	ds_read_b128 v[188:191], v161 offset:3072
	s_add_u32 s2, s2, 0x80000
	s_addc_u32 s3, s3, 0
	s_mov_b32 m0, s40
	v_lshl_add_u64 v[230:231], s[2:3], 0, v[132:133]
	ds_read_b128 v[192:195], v160 offset:32768
	ds_read_b128 v[196:199], v160 offset:33792
	ds_read_b128 v[200:203], v160 offset:34816
	ds_read_b128 v[204:207], v160 offset:35840
	ds_read_b128 v[208:211], v160 offset:36864
	ds_read_b128 v[212:215], v160 offset:37888
	ds_read_b128 v[216:219], v160 offset:38912
	ds_read_b128 v[220:223], v160 offset:39936
	global_load_lds_dwordx4 v[230:231], off
	v_lshl_add_u64 v[230:231], s[2:3], 0, v[136:137]
	s_mov_b32 m0, s41
	s_nop 0
	global_load_lds_dwordx4 v[230:231], off
	s_waitcnt vmcnt(8)
	s_waitcnt lgkmcnt(0)
	s_barrier
	s_setprio 1
	s_waitcnt lgkmcnt(0)
	v_mfma_f32_16x16x32_bf16 v[126:129], v[150:153], v[192:195], v[126:129]
	v_mfma_f32_16x16x32_bf16 v[122:125], v[166:169], v[192:195], v[122:125]
	v_mfma_f32_16x16x32_bf16 v[110:113], v[150:153], v[200:203], v[110:113]
	v_mfma_f32_16x16x32_bf16 v[106:109], v[166:169], v[200:203], v[106:109]
	v_mfma_f32_16x16x32_bf16 v[94:97], v[150:153], v[208:211], v[94:97]
	v_mfma_f32_16x16x32_bf16 v[90:93], v[166:169], v[208:211], v[90:93]
	v_mfma_f32_16x16x32_bf16 v[78:81], v[150:153], v[216:219], v[78:81]
	v_mfma_f32_16x16x32_bf16 v[74:77], v[166:169], v[216:219], v[74:77]
	v_mfma_f32_16x16x32_bf16 v[126:129], v[162:165], v[196:199], v[126:129]
	v_mfma_f32_16x16x32_bf16 v[122:125], v[170:173], v[196:199], v[122:125]
	v_mfma_f32_16x16x32_bf16 v[110:113], v[162:165], v[204:207], v[110:113]
	v_mfma_f32_16x16x32_bf16 v[106:109], v[170:173], v[204:207], v[106:109]
	v_mfma_f32_16x16x32_bf16 v[94:97], v[162:165], v[212:215], v[94:97]
	v_mfma_f32_16x16x32_bf16 v[90:93], v[170:173], v[212:215], v[90:93]
	v_mfma_f32_16x16x32_bf16 v[78:81], v[162:165], v[220:223], v[78:81]
	v_mfma_f32_16x16x32_bf16 v[74:77], v[170:173], v[220:223], v[74:77]
	s_setprio 0
	s_setprio 1
	v_mfma_f32_16x16x32_bf16 v[118:121], v[176:179], v[192:195], v[118:121]
	v_mfma_f32_16x16x32_bf16 v[114:117], v[184:187], v[192:195], v[114:117]
	v_mfma_f32_16x16x32_bf16 v[102:105], v[176:179], v[200:203], v[102:105]
	v_mfma_f32_16x16x32_bf16 v[98:101], v[184:187], v[200:203], v[98:101]
	v_mfma_f32_16x16x32_bf16 v[86:89], v[176:179], v[208:211], v[86:89]
	v_mfma_f32_16x16x32_bf16 v[82:85], v[184:187], v[208:211], v[82:85]
	v_mfma_f32_16x16x32_bf16 v[70:73], v[176:179], v[216:219], v[70:73]
	v_mfma_f32_16x16x32_bf16 v[66:69], v[184:187], v[216:219], v[66:69]
	v_mfma_f32_16x16x32_bf16 v[118:121], v[180:183], v[196:199], v[118:121]
	v_mfma_f32_16x16x32_bf16 v[114:117], v[188:191], v[196:199], v[114:117]
	v_mfma_f32_16x16x32_bf16 v[102:105], v[180:183], v[204:207], v[102:105]
	v_mfma_f32_16x16x32_bf16 v[98:101], v[188:191], v[204:207], v[98:101]
	v_mfma_f32_16x16x32_bf16 v[86:89], v[180:183], v[212:215], v[86:89]
	v_mfma_f32_16x16x32_bf16 v[82:85], v[188:191], v[212:215], v[82:85]
	v_mfma_f32_16x16x32_bf16 v[70:73], v[180:183], v[220:223], v[70:73]
	v_mfma_f32_16x16x32_bf16 v[66:69], v[188:191], v[220:223], v[66:69]
	s_setprio 0
	s_barrier
	s_add_i32 s2, s54, s38
	v_lshl_add_u64 v[154:155], v[154:155], 0, s[16:17]
	s_mov_b32 m0, s2
	ds_read_b128 v[192:195], v160 offset:49152
	ds_read_b128 v[196:199], v160 offset:50176
	ds_read_b128 v[200:203], v160 offset:51200
	ds_read_b128 v[204:207], v160 offset:52224
	ds_read_b128 v[208:211], v160 offset:53248
	ds_read_b128 v[212:215], v160 offset:54272
	ds_read_b128 v[216:219], v160 offset:55296
	ds_read_b128 v[220:223], v160 offset:56320
	global_load_lds_dwordx4 v[154:155], off
	s_add_i32 m0, s2, 0x2000
	s_add_u32 s0, s0, 0x80080
	v_lshl_add_u64 v[154:155], v[224:225], 0, s[16:17]
	s_addc_u32 s1, s1, 0
	s_add_i32 s2, s55, s38
	global_load_lds_dwordx4 v[154:155], off
	v_lshl_add_u64 v[154:155], s[0:1], 0, v[134:135]
	s_mov_b32 m0, s2
	s_nop 0
	global_load_lds_dwordx4 v[154:155], off
	v_lshl_add_u64 v[154:155], s[0:1], 0, v[140:141]
	s_add_i32 m0, s2, 0x2000
	s_nop 0
	global_load_lds_dwordx4 v[154:155], off
	v_lshl_add_u64 v[154:155], v[226:227], 0, s[16:17]
	s_mov_b32 m0, s43
	s_nop 0
	global_load_lds_dwordx4 v[154:155], off
	v_lshl_add_u64 v[154:155], v[228:229], 0, s[16:17]
	s_mov_b32 m0, s44
	s_nop 0
	global_load_lds_dwordx4 v[154:155], off
	s_waitcnt vmcnt(8)
	s_waitcnt lgkmcnt(0)
	s_barrier
	s_setprio 1
	s_waitcnt lgkmcnt(0)
	v_mfma_f32_16x16x32_bf16 v[62:65], v[150:153], v[192:195], v[62:65]
	v_mfma_f32_16x16x32_bf16 v[58:61], v[166:169], v[192:195], v[58:61]
	v_mfma_f32_16x16x32_bf16 v[46:49], v[150:153], v[200:203], v[46:49]
	v_mfma_f32_16x16x32_bf16 v[42:45], v[166:169], v[200:203], v[42:45]
	v_mfma_f32_16x16x32_bf16 v[30:33], v[150:153], v[208:211], v[30:33]
	v_mfma_f32_16x16x32_bf16 v[26:29], v[166:169], v[208:211], v[26:29]
	v_mfma_f32_16x16x32_bf16 v[14:17], v[150:153], v[216:219], v[14:17]
	v_mfma_f32_16x16x32_bf16 v[10:13], v[166:169], v[216:219], v[10:13]
	v_mfma_f32_16x16x32_bf16 v[62:65], v[162:165], v[196:199], v[62:65]
	v_mfma_f32_16x16x32_bf16 v[58:61], v[170:173], v[196:199], v[58:61]
	v_mfma_f32_16x16x32_bf16 v[46:49], v[162:165], v[204:207], v[46:49]
	v_mfma_f32_16x16x32_bf16 v[42:45], v[170:173], v[204:207], v[42:45]
	v_mfma_f32_16x16x32_bf16 v[30:33], v[162:165], v[212:215], v[30:33]
	v_mfma_f32_16x16x32_bf16 v[26:29], v[170:173], v[212:215], v[26:29]
	v_mfma_f32_16x16x32_bf16 v[14:17], v[162:165], v[220:223], v[14:17]
	v_mfma_f32_16x16x32_bf16 v[10:13], v[170:173], v[220:223], v[10:13]
	s_setprio 0
	s_setprio 1
	v_mfma_f32_16x16x32_bf16 v[54:57], v[176:179], v[192:195], v[54:57]
	v_mfma_f32_16x16x32_bf16 v[50:53], v[184:187], v[192:195], v[50:53]
	v_mfma_f32_16x16x32_bf16 v[38:41], v[176:179], v[200:203], v[38:41]
	v_mfma_f32_16x16x32_bf16 v[34:37], v[184:187], v[200:203], v[34:37]
	v_mfma_f32_16x16x32_bf16 v[22:25], v[176:179], v[208:211], v[22:25]
	v_mfma_f32_16x16x32_bf16 v[18:21], v[184:187], v[208:211], v[18:21]
	v_mfma_f32_16x16x32_bf16 v[6:9], v[176:179], v[216:219], v[6:9]
	v_mfma_f32_16x16x32_bf16 v[2:5], v[184:187], v[216:219], v[2:5]
	v_mfma_f32_16x16x32_bf16 v[54:57], v[180:183], v[196:199], v[54:57]
	v_mfma_f32_16x16x32_bf16 v[50:53], v[188:191], v[196:199], v[50:53]
	v_mfma_f32_16x16x32_bf16 v[38:41], v[180:183], v[204:207], v[38:41]
	v_mfma_f32_16x16x32_bf16 v[34:37], v[188:191], v[204:207], v[34:37]
	v_mfma_f32_16x16x32_bf16 v[22:25], v[180:183], v[212:215], v[22:25]
	v_mfma_f32_16x16x32_bf16 v[18:21], v[188:191], v[212:215], v[18:21]
	v_mfma_f32_16x16x32_bf16 v[6:9], v[180:183], v[220:223], v[6:9]
	v_mfma_f32_16x16x32_bf16 v[2:5], v[188:191], v[220:223], v[2:5]
	s_setprio 0
	s_add_i32 s53, s53, 2
	s_add_u32 s30, s30, 0x100
	s_addc_u32 s31, s31, 0
	s_add_u32 s51, s51, 0x100
	s_addc_u32 s52, s52, 0
	s_cmp_gt_u32 s53, 29
	s_barrier
	s_cbranch_scc0 .LBB0_655
	s_and_b64 vcc, exec, s[18:19]
	s_cbranch_vccz .LBB0_658
	s_barrier

.LBB0_740:
	ds_read_b128 v[150:153], v156
	ds_read_b128 v[160:163], v156 offset:1024
	ds_read_b128 v[164:167], v156 offset:2048
	ds_read_b128 v[168:171], v156 offset:3072
	ds_read_b128 v[176:179], v157
	ds_read_b128 v[180:183], v157 offset:1024
	ds_read_b128 v[184:187], v157 offset:2048
	ds_read_b128 v[188:191], v157 offset:3072
	s_add_u32 s0, s30, 0xfff80080
	s_addc_u32 s1, s31, -1
	s_cmp_eq_u32 s51, 28
	s_cselect_b32 s3, s25, s1
	s_cselect_b32 s2, s47, s0
	s_cselect_b32 s1, s23, s50
	s_cselect_b32 s0, s48, s49
	v_lshl_add_u64 v[172:173], s[30:31], 0, v[142:143]
	s_add_i32 m0, s5, 0xc000
	ds_read_b128 v[192:195], v158
	ds_read_b128 v[196:199], v158 offset:1024
	ds_read_b128 v[200:203], v158 offset:2048
	ds_read_b128 v[204:207], v158 offset:3072
	ds_read_b128 v[208:211], v158 offset:4096
	ds_read_b128 v[212:215], v158 offset:5120
	ds_read_b128 v[216:219], v158 offset:6144
	ds_read_b128 v[220:223], v158 offset:7168
	global_load_lds_dwordx4 v[172:173], off
	v_lshl_add_u64 v[172:173], s[30:31], 0, v[144:145]
	s_add_i32 m0, s5, 0xe000
	s_nop 0
	global_load_lds_dwordx4 v[172:173], off
	s_waitcnt vmcnt(8)
	s_waitcnt lgkmcnt(0)
	s_barrier
	s_setprio 1
	s_waitcnt lgkmcnt(0)
	v_mfma_f32_16x16x32_bf16 v[126:129], v[150:153], v[192:195], v[126:129]
	v_mfma_f32_16x16x32_bf16 v[122:125], v[164:167], v[192:195], v[122:125]
	v_mfma_f32_16x16x32_bf16 v[110:113], v[150:153], v[200:203], v[110:113]
	v_mfma_f32_16x16x32_bf16 v[106:109], v[164:167], v[200:203], v[106:109]
	v_mfma_f32_16x16x32_bf16 v[94:97], v[150:153], v[208:211], v[94:97]
	v_mfma_f32_16x16x32_bf16 v[90:93], v[164:167], v[208:211], v[90:93]
	v_mfma_f32_16x16x32_bf16 v[78:81], v[150:153], v[216:219], v[78:81]
	v_mfma_f32_16x16x32_bf16 v[74:77], v[164:167], v[216:219], v[74:77]
	v_mfma_f32_16x16x32_bf16 v[126:129], v[160:163], v[196:199], v[126:129]
	v_mfma_f32_16x16x32_bf16 v[122:125], v[168:171], v[196:199], v[122:125]
	v_mfma_f32_16x16x32_bf16 v[110:113], v[160:163], v[204:207], v[110:113]
	v_mfma_f32_16x16x32_bf16 v[106:109], v[168:171], v[204:207], v[106:109]
	v_mfma_f32_16x16x32_bf16 v[94:97], v[160:163], v[212:215], v[94:97]
	v_mfma_f32_16x16x32_bf16 v[90:93], v[168:171], v[212:215], v[90:93]
	v_mfma_f32_16x16x32_bf16 v[78:81], v[160:163], v[220:223], v[78:81]
	v_mfma_f32_16x16x32_bf16 v[74:77], v[168:171], v[220:223], v[74:77]
	s_setprio 0
	s_setprio 1
	v_mfma_f32_16x16x32_bf16 v[118:121], v[176:179], v[192:195], v[118:121]
	v_mfma_f32_16x16x32_bf16 v[114:117], v[184:187], v[192:195], v[114:117]
	v_mfma_f32_16x16x32_bf16 v[102:105], v[176:179], v[200:203], v[102:105]
	v_mfma_f32_16x16x32_bf16 v[98:101], v[184:187], v[200:203], v[98:101]
	v_mfma_f32_16x16x32_bf16 v[86:89], v[176:179], v[208:211], v[86:89]
	v_mfma_f32_16x16x32_bf16 v[82:85], v[184:187], v[208:211], v[82:85]
	v_mfma_f32_16x16x32_bf16 v[70:73], v[176:179], v[216:219], v[70:73]
	v_mfma_f32_16x16x32_bf16 v[66:69], v[184:187], v[216:219], v[66:69]
	v_mfma_f32_16x16x32_bf16 v[118:121], v[180:183], v[196:199], v[118:121]
	v_mfma_f32_16x16x32_bf16 v[114:117], v[188:191], v[196:199], v[114:117]
	v_mfma_f32_16x16x32_bf16 v[102:105], v[180:183], v[204:207], v[102:105]
	v_mfma_f32_16x16x32_bf16 v[98:101], v[188:191], v[204:207], v[98:101]
	v_mfma_f32_16x16x32_bf16 v[86:89], v[180:183], v[212:215], v[86:89]
	v_mfma_f32_16x16x32_bf16 v[82:85], v[188:191], v[212:215], v[82:85]
	v_mfma_f32_16x16x32_bf16 v[70:73], v[180:183], v[220:223], v[70:73]
	v_mfma_f32_16x16x32_bf16 v[66:69], v[188:191], v[220:223], v[66:69]
	s_setprio 0
	s_barrier
	s_add_i32 s52, s44, s36
	v_lshl_add_u64 v[172:173], s[0:1], 0, v[134:135]
	s_mov_b32 m0, s52
	ds_read_b128 v[192:195], v158 offset:16384
	ds_read_b128 v[196:199], v158 offset:17408
	ds_read_b128 v[200:203], v158 offset:18432
	ds_read_b128 v[204:207], v158 offset:19456
	ds_read_b128 v[208:211], v158 offset:20480
	ds_read_b128 v[212:215], v158 offset:21504
	ds_read_b128 v[216:219], v158 offset:22528
	ds_read_b128 v[220:223], v158 offset:23552
	global_load_lds_dwordx4 v[172:173], off
	s_add_i32 m0, s52, 0x2000
	s_add_u32 s52, s0, 0x80000
	v_lshl_add_u64 v[224:225], s[0:1], 0, v[140:141]
	s_addc_u32 s53, s1, 0
	s_add_i32 s54, s45, s36
	global_load_lds_dwordx4 v[224:225], off
	v_lshl_add_u64 v[226:227], s[52:53], 0, v[134:135]
	s_mov_b32 m0, s54
	v_lshl_add_u64 v[228:229], s[2:3], 0, v[136:137]
	global_load_lds_dwordx4 v[226:227], off
	v_lshl_add_u64 v[226:227], s[52:53], 0, v[140:141]
	s_add_i32 m0, s54, 0x2000
	s_nop 0
	global_load_lds_dwordx4 v[226:227], off
	v_lshl_add_u64 v[226:227], s[2:3], 0, v[132:133]
	s_mov_b32 m0, s5
	s_nop 0
	global_load_lds_dwordx4 v[226:227], off
	s_mov_b32 m0, s37
	s_nop 0
	global_load_lds_dwordx4 v[228:229], off
	s_waitcnt vmcnt(8)
	s_waitcnt lgkmcnt(0)
	s_barrier
	s_setprio 1
	s_waitcnt lgkmcnt(0)
	v_mfma_f32_16x16x32_bf16 v[62:65], v[150:153], v[192:195], v[62:65]
	v_mfma_f32_16x16x32_bf16 v[58:61], v[164:167], v[192:195], v[58:61]
	v_mfma_f32_16x16x32_bf16 v[46:49], v[150:153], v[200:203], v[46:49]
	v_mfma_f32_16x16x32_bf16 v[42:45], v[164:167], v[200:203], v[42:45]
	v_mfma_f32_16x16x32_bf16 v[30:33], v[150:153], v[208:211], v[30:33]
	v_mfma_f32_16x16x32_bf16 v[26:29], v[164:167], v[208:211], v[26:29]
	v_mfma_f32_16x16x32_bf16 v[14:17], v[150:153], v[216:219], v[14:17]
	v_mfma_f32_16x16x32_bf16 v[10:13], v[164:167], v[216:219], v[10:13]
	v_mfma_f32_16x16x32_bf16 v[62:65], v[160:163], v[196:199], v[62:65]
	v_mfma_f32_16x16x32_bf16 v[58:61], v[168:171], v[196:199], v[58:61]
	v_mfma_f32_16x16x32_bf16 v[46:49], v[160:163], v[204:207], v[46:49]
	v_mfma_f32_16x16x32_bf16 v[42:45], v[168:171], v[204:207], v[42:45]
	v_mfma_f32_16x16x32_bf16 v[30:33], v[160:163], v[212:215], v[30:33]
	v_mfma_f32_16x16x32_bf16 v[26:29], v[168:171], v[212:215], v[26:29]
	v_mfma_f32_16x16x32_bf16 v[14:17], v[160:163], v[220:223], v[14:17]
	v_mfma_f32_16x16x32_bf16 v[10:13], v[168:171], v[220:223], v[10:13]
	s_setprio 0
	s_setprio 1
	v_mfma_f32_16x16x32_bf16 v[54:57], v[176:179], v[192:195], v[54:57]
	v_mfma_f32_16x16x32_bf16 v[50:53], v[184:187], v[192:195], v[50:53]
	v_mfma_f32_16x16x32_bf16 v[38:41], v[176:179], v[200:203], v[38:41]
	v_mfma_f32_16x16x32_bf16 v[34:37], v[184:187], v[200:203], v[34:37]
	v_mfma_f32_16x16x32_bf16 v[22:25], v[176:179], v[208:211], v[22:25]
	v_mfma_f32_16x16x32_bf16 v[18:21], v[184:187], v[208:211], v[18:21]
	v_mfma_f32_16x16x32_bf16 v[6:9], v[176:179], v[216:219], v[6:9]
	v_mfma_f32_16x16x32_bf16 v[2:5], v[184:187], v[216:219], v[2:5]
	v_mfma_f32_16x16x32_bf16 v[54:57], v[180:183], v[196:199], v[54:57]
	v_mfma_f32_16x16x32_bf16 v[50:53], v[188:191], v[196:199], v[50:53]
	v_mfma_f32_16x16x32_bf16 v[38:41], v[180:183], v[204:207], v[38:41]
	v_mfma_f32_16x16x32_bf16 v[34:37], v[188:191], v[204:207], v[34:37]
	v_mfma_f32_16x16x32_bf16 v[22:25], v[180:183], v[212:215], v[22:25]
	v_mfma_f32_16x16x32_bf16 v[18:21], v[188:191], v[212:215], v[18:21]
	v_mfma_f32_16x16x32_bf16 v[6:9], v[180:183], v[220:223], v[6:9]
	v_mfma_f32_16x16x32_bf16 v[2:5], v[188:191], v[220:223], v[2:5]
	s_setprio 0
	s_barrier
	s_add_i32 s52, 0, 0x18000
	v_add_u32_e32 v159, s52, v154
	s_add_i32 s53, 0, 0x1c000
	ds_read_b128 v[150:153], v159
	ds_read_b128 v[160:163], v159 offset:1024
	ds_read_b128 v[164:167], v159 offset:2048
	ds_read_b128 v[168:171], v159 offset:3072
	v_add_u32_e32 v159, s53, v154
	ds_read_b128 v[176:179], v159
	ds_read_b128 v[180:183], v159 offset:1024
	ds_read_b128 v[184:187], v159 offset:2048
	ds_read_b128 v[188:191], v159 offset:3072
	s_add_u32 s2, s2, 0x80000
	s_addc_u32 s3, s3, 0
	s_mov_b32 m0, s38
	v_lshl_add_u64 v[230:231], s[2:3], 0, v[132:133]
	ds_read_b128 v[192:195], v158 offset:32768
	ds_read_b128 v[196:199], v158 offset:33792
	ds_read_b128 v[200:203], v158 offset:34816
	ds_read_b128 v[204:207], v158 offset:35840
	ds_read_b128 v[208:211], v158 offset:36864
	ds_read_b128 v[212:215], v158 offset:37888
	ds_read_b128 v[216:219], v158 offset:38912
	ds_read_b128 v[220:223], v158 offset:39936
	global_load_lds_dwordx4 v[230:231], off
	v_lshl_add_u64 v[230:231], s[2:3], 0, v[136:137]
	s_mov_b32 m0, s39
	s_nop 0
	global_load_lds_dwordx4 v[230:231], off
	s_waitcnt vmcnt(8)
	s_waitcnt lgkmcnt(0)
	s_barrier
	s_setprio 1
	s_waitcnt lgkmcnt(0)
	v_mfma_f32_16x16x32_bf16 v[126:129], v[150:153], v[192:195], v[126:129]
	v_mfma_f32_16x16x32_bf16 v[122:125], v[164:167], v[192:195], v[122:125]
	v_mfma_f32_16x16x32_bf16 v[110:113], v[150:153], v[200:203], v[110:113]
	v_mfma_f32_16x16x32_bf16 v[106:109], v[164:167], v[200:203], v[106:109]
	v_mfma_f32_16x16x32_bf16 v[94:97], v[150:153], v[208:211], v[94:97]
	v_mfma_f32_16x16x32_bf16 v[90:93], v[164:167], v[208:211], v[90:93]
	v_mfma_f32_16x16x32_bf16 v[78:81], v[150:153], v[216:219], v[78:81]
	v_mfma_f32_16x16x32_bf16 v[74:77], v[164:167], v[216:219], v[74:77]
	v_mfma_f32_16x16x32_bf16 v[126:129], v[160:163], v[196:199], v[126:129]
	v_mfma_f32_16x16x32_bf16 v[122:125], v[168:171], v[196:199], v[122:125]
	v_mfma_f32_16x16x32_bf16 v[110:113], v[160:163], v[204:207], v[110:113]
	v_mfma_f32_16x16x32_bf16 v[106:109], v[168:171], v[204:207], v[106:109]
	v_mfma_f32_16x16x32_bf16 v[94:97], v[160:163], v[212:215], v[94:97]
	v_mfma_f32_16x16x32_bf16 v[90:93], v[168:171], v[212:215], v[90:93]
	v_mfma_f32_16x16x32_bf16 v[78:81], v[160:163], v[220:223], v[78:81]
	v_mfma_f32_16x16x32_bf16 v[74:77], v[168:171], v[220:223], v[74:77]
	s_setprio 0
	s_setprio 1
	v_mfma_f32_16x16x32_bf16 v[118:121], v[176:179], v[192:195], v[118:121]
	v_mfma_f32_16x16x32_bf16 v[114:117], v[184:187], v[192:195], v[114:117]
	v_mfma_f32_16x16x32_bf16 v[102:105], v[176:179], v[200:203], v[102:105]
	v_mfma_f32_16x16x32_bf16 v[98:101], v[184:187], v[200:203], v[98:101]
	v_mfma_f32_16x16x32_bf16 v[86:89], v[176:179], v[208:211], v[86:89]
	v_mfma_f32_16x16x32_bf16 v[82:85], v[184:187], v[208:211], v[82:85]
	v_mfma_f32_16x16x32_bf16 v[70:73], v[176:179], v[216:219], v[70:73]
	v_mfma_f32_16x16x32_bf16 v[66:69], v[184:187], v[216:219], v[66:69]
	v_mfma_f32_16x16x32_bf16 v[118:121], v[180:183], v[196:199], v[118:121]
	v_mfma_f32_16x16x32_bf16 v[114:117], v[188:191], v[196:199], v[114:117]
	v_mfma_f32_16x16x32_bf16 v[102:105], v[180:183], v[204:207], v[102:105]
	v_mfma_f32_16x16x32_bf16 v[98:101], v[188:191], v[204:207], v[98:101]
	v_mfma_f32_16x16x32_bf16 v[86:89], v[180:183], v[212:215], v[86:89]
	v_mfma_f32_16x16x32_bf16 v[82:85], v[188:191], v[212:215], v[82:85]
	v_mfma_f32_16x16x32_bf16 v[70:73], v[180:183], v[220:223], v[70:73]
	v_mfma_f32_16x16x32_bf16 v[66:69], v[188:191], v[220:223], v[66:69]
	s_setprio 0
	s_barrier
	s_add_i32 s2, s52, s36
	v_lshl_add_u64 v[172:173], v[172:173], 0, s[18:19]
	s_mov_b32 m0, s2
	ds_read_b128 v[192:195], v158 offset:49152
	ds_read_b128 v[196:199], v158 offset:50176
	ds_read_b128 v[200:203], v158 offset:51200
	ds_read_b128 v[204:207], v158 offset:52224
	ds_read_b128 v[208:211], v158 offset:53248
	ds_read_b128 v[212:215], v158 offset:54272
	ds_read_b128 v[216:219], v158 offset:55296
	ds_read_b128 v[220:223], v158 offset:56320
	global_load_lds_dwordx4 v[172:173], off
	s_add_i32 m0, s2, 0x2000
	s_add_u32 s0, s0, 0x80080
	v_lshl_add_u64 v[172:173], v[224:225], 0, s[18:19]
	s_addc_u32 s1, s1, 0
	s_add_i32 s2, s53, s36
	global_load_lds_dwordx4 v[172:173], off
	v_lshl_add_u64 v[172:173], s[0:1], 0, v[134:135]
	s_mov_b32 m0, s2
	s_nop 0
	global_load_lds_dwordx4 v[172:173], off
	v_lshl_add_u64 v[172:173], s[0:1], 0, v[140:141]
	s_add_i32 m0, s2, 0x2000
	s_nop 0
	global_load_lds_dwordx4 v[172:173], off
	v_lshl_add_u64 v[172:173], v[226:227], 0, s[18:19]
	s_mov_b32 m0, s41
	s_nop 0
	global_load_lds_dwordx4 v[172:173], off
	v_lshl_add_u64 v[172:173], v[228:229], 0, s[18:19]
	s_mov_b32 m0, s42
	s_nop 0
	global_load_lds_dwordx4 v[172:173], off
	s_waitcnt vmcnt(8)
	s_waitcnt lgkmcnt(0)
	s_barrier
	s_setprio 1
	s_waitcnt lgkmcnt(0)
	v_mfma_f32_16x16x32_bf16 v[62:65], v[150:153], v[192:195], v[62:65]
	v_mfma_f32_16x16x32_bf16 v[58:61], v[164:167], v[192:195], v[58:61]
	v_mfma_f32_16x16x32_bf16 v[46:49], v[150:153], v[200:203], v[46:49]
	v_mfma_f32_16x16x32_bf16 v[42:45], v[164:167], v[200:203], v[42:45]
	v_mfma_f32_16x16x32_bf16 v[30:33], v[150:153], v[208:211], v[30:33]
	v_mfma_f32_16x16x32_bf16 v[26:29], v[164:167], v[208:211], v[26:29]
	v_mfma_f32_16x16x32_bf16 v[14:17], v[150:153], v[216:219], v[14:17]
	v_mfma_f32_16x16x32_bf16 v[10:13], v[164:167], v[216:219], v[10:13]
	v_mfma_f32_16x16x32_bf16 v[62:65], v[160:163], v[196:199], v[62:65]
	v_mfma_f32_16x16x32_bf16 v[58:61], v[168:171], v[196:199], v[58:61]
	v_mfma_f32_16x16x32_bf16 v[46:49], v[160:163], v[204:207], v[46:49]
	v_mfma_f32_16x16x32_bf16 v[42:45], v[168:171], v[204:207], v[42:45]
	v_mfma_f32_16x16x32_bf16 v[30:33], v[160:163], v[212:215], v[30:33]
	v_mfma_f32_16x16x32_bf16 v[26:29], v[168:171], v[212:215], v[26:29]
	v_mfma_f32_16x16x32_bf16 v[14:17], v[160:163], v[220:223], v[14:17]
	v_mfma_f32_16x16x32_bf16 v[10:13], v[168:171], v[220:223], v[10:13]
	s_setprio 0
	s_setprio 1
	v_mfma_f32_16x16x32_bf16 v[54:57], v[176:179], v[192:195], v[54:57]
	v_mfma_f32_16x16x32_bf16 v[50:53], v[184:187], v[192:195], v[50:53]
	v_mfma_f32_16x16x32_bf16 v[38:41], v[176:179], v[200:203], v[38:41]
	v_mfma_f32_16x16x32_bf16 v[34:37], v[184:187], v[200:203], v[34:37]
	v_mfma_f32_16x16x32_bf16 v[22:25], v[176:179], v[208:211], v[22:25]
	v_mfma_f32_16x16x32_bf16 v[18:21], v[184:187], v[208:211], v[18:21]
	v_mfma_f32_16x16x32_bf16 v[6:9], v[176:179], v[216:219], v[6:9]
	v_mfma_f32_16x16x32_bf16 v[2:5], v[184:187], v[216:219], v[2:5]
	v_mfma_f32_16x16x32_bf16 v[54:57], v[180:183], v[196:199], v[54:57]
	v_mfma_f32_16x16x32_bf16 v[50:53], v[188:191], v[196:199], v[50:53]
	v_mfma_f32_16x16x32_bf16 v[38:41], v[180:183], v[204:207], v[38:41]
	v_mfma_f32_16x16x32_bf16 v[34:37], v[188:191], v[204:207], v[34:37]
	v_mfma_f32_16x16x32_bf16 v[22:25], v[180:183], v[212:215], v[22:25]
	v_mfma_f32_16x16x32_bf16 v[18:21], v[188:191], v[212:215], v[18:21]
	v_mfma_f32_16x16x32_bf16 v[6:9], v[180:183], v[220:223], v[6:9]
	v_mfma_f32_16x16x32_bf16 v[2:5], v[188:191], v[220:223], v[2:5]
	s_setprio 0
	s_add_i32 s51, s51, 2
	s_add_u32 s30, s30, 0x100
	s_addc_u32 s31, s31, 0
	s_add_u32 s49, s49, 0x100
	s_addc_u32 s50, s50, 0
	s_cmp_gt_u32 s51, 29
	s_barrier
	s_cbranch_scc0 .LBB0_740
	s_and_b64 vcc, exec, s[20:21]
	s_cbranch_vccz .LBB0_743
	s_barrier

.LBB0_925:
	ds_read_b128 v[158:161], v180
	ds_read_b128 v[162:165], v180 offset:1024
	ds_read_b128 v[166:169], v180 offset:2048
	ds_read_b128 v[170:173], v180 offset:3072
	ds_read_b128 v[184:187], v181
	ds_read_b128 v[188:191], v181 offset:1024
	ds_read_b128 v[192:195], v181 offset:2048
	ds_read_b128 v[196:199], v181 offset:3072
	s_add_u32 s0, s4, 0xfff80080
	s_addc_u32 s1, s5, -1
	s_cmp_eq_u32 s26, 28
	s_cselect_b32 s3, s9, s1
	s_cselect_b32 s2, s8, s0
	s_cselect_b32 s1, s25, s23
	s_cselect_b32 s0, s24, s14
	v_lshl_add_u64 v[232:233], s[4:5], 0, v[150:151]
	s_add_i32 m0, s28, 0xc000
	ds_read_b128 v[200:203], v182
	ds_read_b128 v[204:207], v182 offset:1024
	ds_read_b128 v[208:211], v182 offset:2048
	ds_read_b128 v[212:215], v182 offset:3072
	ds_read_b128 v[216:219], v182 offset:4096
	ds_read_b128 v[220:223], v182 offset:5120
	ds_read_b128 v[224:227], v182 offset:6144
	ds_read_b128 v[228:231], v182 offset:7168
	global_load_lds_dwordx4 v[232:233], off
	v_lshl_add_u64 v[232:233], s[4:5], 0, v[152:153]
	s_add_i32 m0, s28, 0xe000
	s_nop 0
	global_load_lds_dwordx4 v[232:233], off
	s_waitcnt vmcnt(8)
	s_waitcnt lgkmcnt(0)
	s_barrier
	s_setprio 1
	s_waitcnt lgkmcnt(0)
	v_mfma_f32_16x16x32_bf16 v[126:129], v[158:161], v[200:203], v[126:129]
	v_mfma_f32_16x16x32_bf16 v[122:125], v[166:169], v[200:203], v[122:125]
	v_mfma_f32_16x16x32_bf16 v[118:121], v[158:161], v[208:211], v[118:121]
	v_mfma_f32_16x16x32_bf16 v[114:117], v[166:169], v[208:211], v[114:117]
	v_mfma_f32_16x16x32_bf16 v[102:105], v[158:161], v[216:219], v[102:105]
	v_mfma_f32_16x16x32_bf16 v[98:101], v[166:169], v[216:219], v[98:101]
	v_mfma_f32_16x16x32_bf16 v[86:89], v[158:161], v[224:227], v[86:89]
	v_mfma_f32_16x16x32_bf16 v[82:85], v[166:169], v[224:227], v[82:85]
	v_mfma_f32_16x16x32_bf16 v[126:129], v[162:165], v[204:207], v[126:129]
	v_mfma_f32_16x16x32_bf16 v[122:125], v[170:173], v[204:207], v[122:125]
	v_mfma_f32_16x16x32_bf16 v[118:121], v[162:165], v[212:215], v[118:121]
	v_mfma_f32_16x16x32_bf16 v[114:117], v[170:173], v[212:215], v[114:117]
	v_mfma_f32_16x16x32_bf16 v[102:105], v[162:165], v[220:223], v[102:105]
	v_mfma_f32_16x16x32_bf16 v[98:101], v[170:173], v[220:223], v[98:101]
	v_mfma_f32_16x16x32_bf16 v[86:89], v[162:165], v[228:231], v[86:89]
	v_mfma_f32_16x16x32_bf16 v[82:85], v[170:173], v[228:231], v[82:85]
	s_setprio 0
	s_setprio 1
	v_mfma_f32_16x16x32_bf16 v[110:113], v[184:187], v[200:203], v[110:113]
	v_mfma_f32_16x16x32_bf16 v[106:109], v[192:195], v[200:203], v[106:109]
	v_mfma_f32_16x16x32_bf16 v[94:97], v[184:187], v[208:211], v[94:97]
	v_mfma_f32_16x16x32_bf16 v[90:93], v[192:195], v[208:211], v[90:93]
	v_mfma_f32_16x16x32_bf16 v[78:81], v[184:187], v[216:219], v[78:81]
	v_mfma_f32_16x16x32_bf16 v[74:77], v[192:195], v[216:219], v[74:77]
	v_mfma_f32_16x16x32_bf16 v[70:73], v[184:187], v[224:227], v[70:73]
	v_mfma_f32_16x16x32_bf16 v[66:69], v[192:195], v[224:227], v[66:69]
	v_mfma_f32_16x16x32_bf16 v[110:113], v[188:191], v[204:207], v[110:113]
	v_mfma_f32_16x16x32_bf16 v[106:109], v[196:199], v[204:207], v[106:109]
	v_mfma_f32_16x16x32_bf16 v[94:97], v[188:191], v[212:215], v[94:97]
	v_mfma_f32_16x16x32_bf16 v[90:93], v[196:199], v[212:215], v[90:93]
	v_mfma_f32_16x16x32_bf16 v[78:81], v[188:191], v[220:223], v[78:81]
	v_mfma_f32_16x16x32_bf16 v[74:77], v[196:199], v[220:223], v[74:77]
	v_mfma_f32_16x16x32_bf16 v[70:73], v[188:191], v[228:231], v[70:73]
	v_mfma_f32_16x16x32_bf16 v[66:69], v[196:199], v[228:231], v[66:69]
	s_setprio 0
	s_barrier
	s_add_i32 s27, s47, s13
	v_lshl_add_u64 v[232:233], s[0:1], 0, v[136:137]
	s_mov_b32 m0, s27
	ds_read_b128 v[200:203], v182 offset:16384
	ds_read_b128 v[204:207], v182 offset:17408
	ds_read_b128 v[208:211], v182 offset:18432
	ds_read_b128 v[212:215], v182 offset:19456
	ds_read_b128 v[216:219], v182 offset:20480
	ds_read_b128 v[220:223], v182 offset:21504
	ds_read_b128 v[224:227], v182 offset:22528
	ds_read_b128 v[228:231], v182 offset:23552
	global_load_lds_dwordx4 v[232:233], off
	s_add_i32 m0, s27, 0x2000
	s_add_u32 s54, s0, 0x80000
	v_lshl_add_u64 v[234:235], s[0:1], 0, v[142:143]
	s_addc_u32 s55, s1, 0
	s_add_i32 s27, s48, s13
	global_load_lds_dwordx4 v[234:235], off
	v_lshl_add_u64 v[236:237], s[54:55], 0, v[136:137]
	s_mov_b32 m0, s27
	v_lshl_add_u64 v[238:239], s[2:3], 0, v[140:141]
	global_load_lds_dwordx4 v[236:237], off
	v_lshl_add_u64 v[236:237], s[54:55], 0, v[142:143]
	s_add_i32 m0, s27, 0x2000
	s_nop 0
	global_load_lds_dwordx4 v[236:237], off
	v_lshl_add_u64 v[236:237], s[2:3], 0, v[134:135]
	s_mov_b32 m0, s28
	s_nop 0
	global_load_lds_dwordx4 v[236:237], off
	s_mov_b32 m0, s29
	s_nop 0
	global_load_lds_dwordx4 v[238:239], off
	s_waitcnt vmcnt(8)
	s_waitcnt lgkmcnt(0)
	s_barrier
	s_setprio 1
	s_waitcnt lgkmcnt(0)
	v_mfma_f32_16x16x32_bf16 v[62:65], v[158:161], v[200:203], v[62:65]
	v_mfma_f32_16x16x32_bf16 v[58:61], v[166:169], v[200:203], v[58:61]
	v_mfma_f32_16x16x32_bf16 v[54:57], v[158:161], v[208:211], v[54:57]
	v_mfma_f32_16x16x32_bf16 v[50:53], v[166:169], v[208:211], v[50:53]
	v_mfma_f32_16x16x32_bf16 v[38:41], v[158:161], v[216:219], v[38:41]
	v_mfma_f32_16x16x32_bf16 v[34:37], v[166:169], v[216:219], v[34:37]
	v_mfma_f32_16x16x32_bf16 v[22:25], v[158:161], v[224:227], v[22:25]
	v_mfma_f32_16x16x32_bf16 v[18:21], v[166:169], v[224:227], v[18:21]
	v_mfma_f32_16x16x32_bf16 v[62:65], v[162:165], v[204:207], v[62:65]
	v_mfma_f32_16x16x32_bf16 v[58:61], v[170:173], v[204:207], v[58:61]
	v_mfma_f32_16x16x32_bf16 v[54:57], v[162:165], v[212:215], v[54:57]
	v_mfma_f32_16x16x32_bf16 v[50:53], v[170:173], v[212:215], v[50:53]
	v_mfma_f32_16x16x32_bf16 v[38:41], v[162:165], v[220:223], v[38:41]
	v_mfma_f32_16x16x32_bf16 v[34:37], v[170:173], v[220:223], v[34:37]
	v_mfma_f32_16x16x32_bf16 v[22:25], v[162:165], v[228:231], v[22:25]
	v_mfma_f32_16x16x32_bf16 v[18:21], v[170:173], v[228:231], v[18:21]
	s_setprio 0
	s_setprio 1
	v_mfma_f32_16x16x32_bf16 v[46:49], v[184:187], v[200:203], v[46:49]
	v_mfma_f32_16x16x32_bf16 v[42:45], v[192:195], v[200:203], v[42:45]
	v_mfma_f32_16x16x32_bf16 v[30:33], v[184:187], v[208:211], v[30:33]
	v_mfma_f32_16x16x32_bf16 v[26:29], v[192:195], v[208:211], v[26:29]
	v_mfma_f32_16x16x32_bf16 v[14:17], v[184:187], v[216:219], v[14:17]
	v_mfma_f32_16x16x32_bf16 v[10:13], v[192:195], v[216:219], v[10:13]
	v_mfma_f32_16x16x32_bf16 v[6:9], v[184:187], v[224:227], v[6:9]
	v_mfma_f32_16x16x32_bf16 v[2:5], v[192:195], v[224:227], v[2:5]
	v_mfma_f32_16x16x32_bf16 v[46:49], v[188:191], v[204:207], v[46:49]
	v_mfma_f32_16x16x32_bf16 v[42:45], v[196:199], v[204:207], v[42:45]
	v_mfma_f32_16x16x32_bf16 v[30:33], v[188:191], v[212:215], v[30:33]
	v_mfma_f32_16x16x32_bf16 v[26:29], v[196:199], v[212:215], v[26:29]
	v_mfma_f32_16x16x32_bf16 v[14:17], v[188:191], v[220:223], v[14:17]
	v_mfma_f32_16x16x32_bf16 v[10:13], v[196:199], v[220:223], v[10:13]
	v_mfma_f32_16x16x32_bf16 v[6:9], v[188:191], v[228:231], v[6:9]
	v_mfma_f32_16x16x32_bf16 v[2:5], v[196:199], v[228:231], v[2:5]
	s_setprio 0
	s_barrier
	s_add_i32 s27, 0, 0x18000
	v_add_u32_e32 v144, s27, v179
	s_add_i32 s53, 0, 0x1c000
	ds_read_b128 v[158:161], v144
	ds_read_b128 v[162:165], v144 offset:1024
	ds_read_b128 v[166:169], v144 offset:2048
	ds_read_b128 v[170:173], v144 offset:3072
	v_add_u32_e32 v144, s53, v179
	ds_read_b128 v[184:187], v144
	ds_read_b128 v[188:191], v144 offset:1024
	ds_read_b128 v[192:195], v144 offset:2048
	ds_read_b128 v[196:199], v144 offset:3072
	s_add_u32 s2, s2, 0x80000
	s_addc_u32 s3, s3, 0
	s_mov_b32 m0, s30
	v_lshl_add_u64 v[240:241], s[2:3], 0, v[134:135]
	ds_read_b128 v[200:203], v182 offset:32768
	ds_read_b128 v[204:207], v182 offset:33792
	ds_read_b128 v[208:211], v182 offset:34816
	ds_read_b128 v[212:215], v182 offset:35840
	ds_read_b128 v[216:219], v182 offset:36864
	ds_read_b128 v[220:223], v182 offset:37888
	ds_read_b128 v[224:227], v182 offset:38912
	ds_read_b128 v[228:231], v182 offset:39936
	global_load_lds_dwordx4 v[240:241], off
	v_lshl_add_u64 v[240:241], s[2:3], 0, v[140:141]
	s_mov_b32 m0, s31
	s_nop 0
	global_load_lds_dwordx4 v[240:241], off
	s_waitcnt vmcnt(8)
	s_waitcnt lgkmcnt(0)
	s_barrier
	s_setprio 1
	s_waitcnt lgkmcnt(0)
	v_mfma_f32_16x16x32_bf16 v[126:129], v[158:161], v[200:203], v[126:129]
	v_mfma_f32_16x16x32_bf16 v[122:125], v[166:169], v[200:203], v[122:125]
	v_mfma_f32_16x16x32_bf16 v[118:121], v[158:161], v[208:211], v[118:121]
	v_mfma_f32_16x16x32_bf16 v[114:117], v[166:169], v[208:211], v[114:117]
	v_mfma_f32_16x16x32_bf16 v[102:105], v[158:161], v[216:219], v[102:105]
	v_mfma_f32_16x16x32_bf16 v[98:101], v[166:169], v[216:219], v[98:101]
	v_mfma_f32_16x16x32_bf16 v[86:89], v[158:161], v[224:227], v[86:89]
	v_mfma_f32_16x16x32_bf16 v[82:85], v[166:169], v[224:227], v[82:85]
	v_mfma_f32_16x16x32_bf16 v[126:129], v[162:165], v[204:207], v[126:129]
	v_mfma_f32_16x16x32_bf16 v[122:125], v[170:173], v[204:207], v[122:125]
	v_mfma_f32_16x16x32_bf16 v[118:121], v[162:165], v[212:215], v[118:121]
	v_mfma_f32_16x16x32_bf16 v[114:117], v[170:173], v[212:215], v[114:117]
	v_mfma_f32_16x16x32_bf16 v[102:105], v[162:165], v[220:223], v[102:105]
	v_mfma_f32_16x16x32_bf16 v[98:101], v[170:173], v[220:223], v[98:101]
	v_mfma_f32_16x16x32_bf16 v[86:89], v[162:165], v[228:231], v[86:89]
	v_mfma_f32_16x16x32_bf16 v[82:85], v[170:173], v[228:231], v[82:85]
	s_setprio 0
	s_setprio 1
	v_mfma_f32_16x16x32_bf16 v[110:113], v[184:187], v[200:203], v[110:113]
	v_mfma_f32_16x16x32_bf16 v[106:109], v[192:195], v[200:203], v[106:109]
	v_mfma_f32_16x16x32_bf16 v[94:97], v[184:187], v[208:211], v[94:97]
	v_mfma_f32_16x16x32_bf16 v[90:93], v[192:195], v[208:211], v[90:93]
	v_mfma_f32_16x16x32_bf16 v[78:81], v[184:187], v[216:219], v[78:81]
	v_mfma_f32_16x16x32_bf16 v[74:77], v[192:195], v[216:219], v[74:77]
	v_mfma_f32_16x16x32_bf16 v[70:73], v[184:187], v[224:227], v[70:73]
	v_mfma_f32_16x16x32_bf16 v[66:69], v[192:195], v[224:227], v[66:69]
	v_mfma_f32_16x16x32_bf16 v[110:113], v[188:191], v[204:207], v[110:113]
	v_mfma_f32_16x16x32_bf16 v[106:109], v[196:199], v[204:207], v[106:109]
	v_mfma_f32_16x16x32_bf16 v[94:97], v[188:191], v[212:215], v[94:97]
	v_mfma_f32_16x16x32_bf16 v[90:93], v[196:199], v[212:215], v[90:93]
	v_mfma_f32_16x16x32_bf16 v[78:81], v[188:191], v[220:223], v[78:81]
	v_mfma_f32_16x16x32_bf16 v[74:77], v[196:199], v[220:223], v[74:77]
	v_mfma_f32_16x16x32_bf16 v[70:73], v[188:191], v[228:231], v[70:73]
	v_mfma_f32_16x16x32_bf16 v[66:69], v[196:199], v[228:231], v[66:69]
	s_setprio 0
	s_barrier
	s_add_i32 s2, s27, s13
	v_lshl_add_u64 v[232:233], v[232:233], 0, s[18:19]
	s_mov_b32 m0, s2
	ds_read_b128 v[200:203], v182 offset:49152
	ds_read_b128 v[204:207], v182 offset:50176
	ds_read_b128 v[208:211], v182 offset:51200
	ds_read_b128 v[212:215], v182 offset:52224
	ds_read_b128 v[216:219], v182 offset:53248
	ds_read_b128 v[220:223], v182 offset:54272
	ds_read_b128 v[224:227], v182 offset:55296
	ds_read_b128 v[228:231], v182 offset:56320
	global_load_lds_dwordx4 v[232:233], off
	s_add_i32 m0, s2, 0x2000
	s_add_u32 s0, s0, 0x80080
	v_lshl_add_u64 v[232:233], v[234:235], 0, s[18:19]
	s_addc_u32 s1, s1, 0
	s_add_i32 s2, s53, s13
	global_load_lds_dwordx4 v[232:233], off
	v_lshl_add_u64 v[232:233], s[0:1], 0, v[136:137]
	s_mov_b32 m0, s2
	s_nop 0
	global_load_lds_dwordx4 v[232:233], off
	v_lshl_add_u64 v[232:233], s[0:1], 0, v[142:143]
	s_add_i32 m0, s2, 0x2000
	s_nop 0
	global_load_lds_dwordx4 v[232:233], off
	v_lshl_add_u64 v[232:233], v[236:237], 0, s[18:19]
	s_mov_b32 m0, s33
	s_nop 0
	global_load_lds_dwordx4 v[232:233], off
	v_lshl_add_u64 v[232:233], v[238:239], 0, s[18:19]
	s_mov_b32 m0, s34
	s_nop 0
	global_load_lds_dwordx4 v[232:233], off
	s_waitcnt vmcnt(8)
	s_waitcnt lgkmcnt(0)
	s_barrier
	s_setprio 1
	s_waitcnt lgkmcnt(0)
	v_mfma_f32_16x16x32_bf16 v[62:65], v[158:161], v[200:203], v[62:65]
	v_mfma_f32_16x16x32_bf16 v[58:61], v[166:169], v[200:203], v[58:61]
	v_mfma_f32_16x16x32_bf16 v[54:57], v[158:161], v[208:211], v[54:57]
	v_mfma_f32_16x16x32_bf16 v[50:53], v[166:169], v[208:211], v[50:53]
	v_mfma_f32_16x16x32_bf16 v[38:41], v[158:161], v[216:219], v[38:41]
	v_mfma_f32_16x16x32_bf16 v[34:37], v[166:169], v[216:219], v[34:37]
	v_mfma_f32_16x16x32_bf16 v[22:25], v[158:161], v[224:227], v[22:25]
	v_mfma_f32_16x16x32_bf16 v[18:21], v[166:169], v[224:227], v[18:21]
	v_mfma_f32_16x16x32_bf16 v[62:65], v[162:165], v[204:207], v[62:65]
	v_mfma_f32_16x16x32_bf16 v[58:61], v[170:173], v[204:207], v[58:61]
	v_mfma_f32_16x16x32_bf16 v[54:57], v[162:165], v[212:215], v[54:57]
	v_mfma_f32_16x16x32_bf16 v[50:53], v[170:173], v[212:215], v[50:53]
	v_mfma_f32_16x16x32_bf16 v[38:41], v[162:165], v[220:223], v[38:41]
	v_mfma_f32_16x16x32_bf16 v[34:37], v[170:173], v[220:223], v[34:37]
	v_mfma_f32_16x16x32_bf16 v[22:25], v[162:165], v[228:231], v[22:25]
	v_mfma_f32_16x16x32_bf16 v[18:21], v[170:173], v[228:231], v[18:21]
	s_setprio 0
	s_setprio 1
	v_mfma_f32_16x16x32_bf16 v[46:49], v[184:187], v[200:203], v[46:49]
	v_mfma_f32_16x16x32_bf16 v[42:45], v[192:195], v[200:203], v[42:45]
	v_mfma_f32_16x16x32_bf16 v[30:33], v[184:187], v[208:211], v[30:33]
	v_mfma_f32_16x16x32_bf16 v[26:29], v[192:195], v[208:211], v[26:29]
	v_mfma_f32_16x16x32_bf16 v[14:17], v[184:187], v[216:219], v[14:17]
	v_mfma_f32_16x16x32_bf16 v[10:13], v[192:195], v[216:219], v[10:13]
	v_mfma_f32_16x16x32_bf16 v[6:9], v[184:187], v[224:227], v[6:9]
	v_mfma_f32_16x16x32_bf16 v[2:5], v[192:195], v[224:227], v[2:5]
	v_mfma_f32_16x16x32_bf16 v[46:49], v[188:191], v[204:207], v[46:49]
	v_mfma_f32_16x16x32_bf16 v[42:45], v[196:199], v[204:207], v[42:45]
	v_mfma_f32_16x16x32_bf16 v[30:33], v[188:191], v[212:215], v[30:33]
	v_mfma_f32_16x16x32_bf16 v[26:29], v[196:199], v[212:215], v[26:29]
	v_mfma_f32_16x16x32_bf16 v[14:17], v[188:191], v[220:223], v[14:17]
	v_mfma_f32_16x16x32_bf16 v[10:13], v[196:199], v[220:223], v[10:13]
	v_mfma_f32_16x16x32_bf16 v[6:9], v[188:191], v[228:231], v[6:9]
	v_mfma_f32_16x16x32_bf16 v[2:5], v[196:199], v[228:231], v[2:5]
	s_setprio 0
	s_add_i32 s26, s26, 2
	s_add_u32 s4, s4, 0x100
	s_addc_u32 s5, s5, 0
	s_add_u32 s14, s14, 0x100
	s_addc_u32 s23, s23, 0
	s_cmp_gt_u32 s26, 29
	s_barrier
	s_cbranch_scc0 .LBB0_925
	s_and_b64 vcc, exec, s[20:21]
	s_cbranch_vccz .LBB0_928
	s_barrier

.LBB0_1261:
	ds_read_b128 v[130:133], v164
	ds_read_b128 v[134:137], v164 offset:1024
	ds_read_b128 v[158:161], v164 offset:2048
	ds_read_b128 v[168:171], v164 offset:3072
	ds_read_b128 v[176:179], v165
	ds_read_b128 v[180:183], v165 offset:1024
	ds_read_b128 v[184:187], v165 offset:2048
	ds_read_b128 v[188:191], v165 offset:3072
	s_add_u32 s0, s28, 0xfff80080
	s_addc_u32 s1, s29, -1
	s_cmp_eq_u32 s51, 28
	s_cselect_b32 s3, s21, s1
	s_cselect_b32 s2, s47, s0
	s_cselect_b32 s1, s19, s50
	s_cselect_b32 s0, s48, s49
	v_lshl_add_u64 v[172:173], s[28:29], 0, v[150:151]
	s_add_i32 m0, s27, 0xc000
	ds_read_b128 v[192:195], v166
	ds_read_b128 v[196:199], v166 offset:1024
	ds_read_b128 v[200:203], v166 offset:2048
	ds_read_b128 v[204:207], v166 offset:3072
	ds_read_b128 v[208:211], v166 offset:4096
	ds_read_b128 v[212:215], v166 offset:5120
	ds_read_b128 v[216:219], v166 offset:6144
	ds_read_b128 v[220:223], v166 offset:7168
	global_load_lds_dwordx4 v[172:173], off
	v_lshl_add_u64 v[172:173], s[28:29], 0, v[152:153]
	s_add_i32 m0, s27, 0xe000
	s_nop 0
	global_load_lds_dwordx4 v[172:173], off
	s_waitcnt vmcnt(8)
	s_waitcnt lgkmcnt(0)
	s_barrier
	s_setprio 1
	s_waitcnt lgkmcnt(0)
	v_mfma_f32_16x16x32_bf16 v[126:129], v[130:133], v[192:195], v[126:129]
	v_mfma_f32_16x16x32_bf16 v[122:125], v[158:161], v[192:195], v[122:125]
	v_mfma_f32_16x16x32_bf16 v[118:121], v[130:133], v[200:203], v[118:121]
	v_mfma_f32_16x16x32_bf16 v[110:113], v[158:161], v[200:203], v[110:113]
	v_mfma_f32_16x16x32_bf16 v[102:105], v[130:133], v[208:211], v[102:105]
	v_mfma_f32_16x16x32_bf16 v[94:97], v[158:161], v[208:211], v[94:97]
	v_mfma_f32_16x16x32_bf16 v[86:89], v[130:133], v[216:219], v[86:89]
	v_mfma_f32_16x16x32_bf16 v[78:81], v[158:161], v[216:219], v[78:81]
	v_mfma_f32_16x16x32_bf16 v[126:129], v[134:137], v[196:199], v[126:129]
	v_mfma_f32_16x16x32_bf16 v[122:125], v[168:171], v[196:199], v[122:125]
	v_mfma_f32_16x16x32_bf16 v[118:121], v[134:137], v[204:207], v[118:121]
	v_mfma_f32_16x16x32_bf16 v[110:113], v[168:171], v[204:207], v[110:113]
	v_mfma_f32_16x16x32_bf16 v[102:105], v[134:137], v[212:215], v[102:105]
	v_mfma_f32_16x16x32_bf16 v[94:97], v[168:171], v[212:215], v[94:97]
	v_mfma_f32_16x16x32_bf16 v[86:89], v[134:137], v[220:223], v[86:89]
	v_mfma_f32_16x16x32_bf16 v[78:81], v[168:171], v[220:223], v[78:81]
	s_setprio 0
	s_setprio 1
	v_mfma_f32_16x16x32_bf16 v[114:117], v[176:179], v[192:195], v[114:117]
	v_mfma_f32_16x16x32_bf16 v[106:109], v[184:187], v[192:195], v[106:109]
	v_mfma_f32_16x16x32_bf16 v[98:101], v[176:179], v[200:203], v[98:101]
	v_mfma_f32_16x16x32_bf16 v[90:93], v[184:187], v[200:203], v[90:93]
	v_mfma_f32_16x16x32_bf16 v[82:85], v[176:179], v[208:211], v[82:85]
	v_mfma_f32_16x16x32_bf16 v[74:77], v[184:187], v[208:211], v[74:77]
	v_mfma_f32_16x16x32_bf16 v[70:73], v[176:179], v[216:219], v[70:73]
	v_mfma_f32_16x16x32_bf16 v[66:69], v[184:187], v[216:219], v[66:69]
	v_mfma_f32_16x16x32_bf16 v[114:117], v[180:183], v[196:199], v[114:117]
	v_mfma_f32_16x16x32_bf16 v[106:109], v[188:191], v[196:199], v[106:109]
	v_mfma_f32_16x16x32_bf16 v[98:101], v[180:183], v[204:207], v[98:101]
	v_mfma_f32_16x16x32_bf16 v[90:93], v[188:191], v[204:207], v[90:93]
	v_mfma_f32_16x16x32_bf16 v[82:85], v[180:183], v[212:215], v[82:85]
	v_mfma_f32_16x16x32_bf16 v[74:77], v[188:191], v[212:215], v[74:77]
	v_mfma_f32_16x16x32_bf16 v[70:73], v[180:183], v[220:223], v[70:73]
	v_mfma_f32_16x16x32_bf16 v[66:69], v[188:191], v[220:223], v[66:69]
	s_setprio 0
	s_barrier
	s_add_i32 s52, s44, s36
	v_lshl_add_u64 v[172:173], s[0:1], 0, v[144:145]
	s_mov_b32 m0, s52
	ds_read_b128 v[192:195], v166 offset:16384
	ds_read_b128 v[196:199], v166 offset:17408
	ds_read_b128 v[200:203], v166 offset:18432
	ds_read_b128 v[204:207], v166 offset:19456
	ds_read_b128 v[208:211], v166 offset:20480
	ds_read_b128 v[212:215], v166 offset:21504
	ds_read_b128 v[216:219], v166 offset:22528
	ds_read_b128 v[220:223], v166 offset:23552
	global_load_lds_dwordx4 v[172:173], off
	s_add_i32 m0, s52, 0x2000
	s_add_u32 s52, s0, 0x80000
	v_lshl_add_u64 v[224:225], s[0:1], 0, v[148:149]
	s_addc_u32 s53, s1, 0
	s_add_i32 s54, s45, s36
	global_load_lds_dwordx4 v[224:225], off
	v_lshl_add_u64 v[226:227], s[52:53], 0, v[144:145]
	s_mov_b32 m0, s54
	v_lshl_add_u64 v[228:229], s[2:3], 0, v[146:147]
	global_load_lds_dwordx4 v[226:227], off
	v_lshl_add_u64 v[226:227], s[52:53], 0, v[148:149]
	s_add_i32 m0, s54, 0x2000
	s_nop 0
	global_load_lds_dwordx4 v[226:227], off
	v_lshl_add_u64 v[226:227], s[2:3], 0, v[142:143]
	s_mov_b32 m0, s27
	s_nop 0
	global_load_lds_dwordx4 v[226:227], off
	s_mov_b32 m0, s37
	s_nop 0
	global_load_lds_dwordx4 v[228:229], off
	s_waitcnt vmcnt(8)
	s_waitcnt lgkmcnt(0)
	s_barrier
	s_setprio 1
	s_waitcnt lgkmcnt(0)
	v_mfma_f32_16x16x32_bf16 v[62:65], v[130:133], v[192:195], v[62:65]
	v_mfma_f32_16x16x32_bf16 v[58:61], v[158:161], v[192:195], v[58:61]
	v_mfma_f32_16x16x32_bf16 v[46:49], v[130:133], v[200:203], v[46:49]
	v_mfma_f32_16x16x32_bf16 v[42:45], v[158:161], v[200:203], v[42:45]
	v_mfma_f32_16x16x32_bf16 v[30:33], v[130:133], v[208:211], v[30:33]
	v_mfma_f32_16x16x32_bf16 v[26:29], v[158:161], v[208:211], v[26:29]
	v_mfma_f32_16x16x32_bf16 v[14:17], v[130:133], v[216:219], v[14:17]
	v_mfma_f32_16x16x32_bf16 v[10:13], v[158:161], v[216:219], v[10:13]
	v_mfma_f32_16x16x32_bf16 v[62:65], v[134:137], v[196:199], v[62:65]
	v_mfma_f32_16x16x32_bf16 v[58:61], v[168:171], v[196:199], v[58:61]
	v_mfma_f32_16x16x32_bf16 v[46:49], v[134:137], v[204:207], v[46:49]
	v_mfma_f32_16x16x32_bf16 v[42:45], v[168:171], v[204:207], v[42:45]
	v_mfma_f32_16x16x32_bf16 v[30:33], v[134:137], v[212:215], v[30:33]
	v_mfma_f32_16x16x32_bf16 v[26:29], v[168:171], v[212:215], v[26:29]
	v_mfma_f32_16x16x32_bf16 v[14:17], v[134:137], v[220:223], v[14:17]
	v_mfma_f32_16x16x32_bf16 v[10:13], v[168:171], v[220:223], v[10:13]
	s_setprio 0
	s_setprio 1
	v_mfma_f32_16x16x32_bf16 v[54:57], v[176:179], v[192:195], v[54:57]
	v_mfma_f32_16x16x32_bf16 v[50:53], v[184:187], v[192:195], v[50:53]
	v_mfma_f32_16x16x32_bf16 v[38:41], v[176:179], v[200:203], v[38:41]
	v_mfma_f32_16x16x32_bf16 v[34:37], v[184:187], v[200:203], v[34:37]
	v_mfma_f32_16x16x32_bf16 v[22:25], v[176:179], v[208:211], v[22:25]
	v_mfma_f32_16x16x32_bf16 v[18:21], v[184:187], v[208:211], v[18:21]
	v_mfma_f32_16x16x32_bf16 v[6:9], v[176:179], v[216:219], v[6:9]
	v_mfma_f32_16x16x32_bf16 v[2:5], v[184:187], v[216:219], v[2:5]
	v_mfma_f32_16x16x32_bf16 v[54:57], v[180:183], v[196:199], v[54:57]
	v_mfma_f32_16x16x32_bf16 v[50:53], v[188:191], v[196:199], v[50:53]
	v_mfma_f32_16x16x32_bf16 v[38:41], v[180:183], v[204:207], v[38:41]
	v_mfma_f32_16x16x32_bf16 v[34:37], v[188:191], v[204:207], v[34:37]
	v_mfma_f32_16x16x32_bf16 v[22:25], v[180:183], v[212:215], v[22:25]
	v_mfma_f32_16x16x32_bf16 v[18:21], v[188:191], v[212:215], v[18:21]
	v_mfma_f32_16x16x32_bf16 v[6:9], v[180:183], v[220:223], v[6:9]
	v_mfma_f32_16x16x32_bf16 v[2:5], v[188:191], v[220:223], v[2:5]
	s_setprio 0
	s_barrier
	s_add_i32 s52, 0, 0x18000
	v_add_u32_e32 v167, s52, v162
	s_add_i32 s53, 0, 0x1c000
	ds_read_b128 v[130:133], v167
	ds_read_b128 v[134:137], v167 offset:1024
	ds_read_b128 v[158:161], v167 offset:2048
	ds_read_b128 v[168:171], v167 offset:3072
	v_add_u32_e32 v167, s53, v162
	ds_read_b128 v[176:179], v167
	ds_read_b128 v[180:183], v167 offset:1024
	ds_read_b128 v[184:187], v167 offset:2048
	ds_read_b128 v[188:191], v167 offset:3072
	s_add_u32 s2, s2, 0x80000
	s_addc_u32 s3, s3, 0
	s_mov_b32 m0, s38
	v_lshl_add_u64 v[230:231], s[2:3], 0, v[142:143]
	ds_read_b128 v[192:195], v166 offset:32768
	ds_read_b128 v[196:199], v166 offset:33792
	ds_read_b128 v[200:203], v166 offset:34816
	ds_read_b128 v[204:207], v166 offset:35840
	ds_read_b128 v[208:211], v166 offset:36864
	ds_read_b128 v[212:215], v166 offset:37888
	ds_read_b128 v[216:219], v166 offset:38912
	ds_read_b128 v[220:223], v166 offset:39936
	global_load_lds_dwordx4 v[230:231], off
	v_lshl_add_u64 v[230:231], s[2:3], 0, v[146:147]
	s_mov_b32 m0, s39
	s_nop 0
	global_load_lds_dwordx4 v[230:231], off
	s_waitcnt vmcnt(8)
	s_waitcnt lgkmcnt(0)
	s_barrier
	s_setprio 1
	s_waitcnt lgkmcnt(0)
	v_mfma_f32_16x16x32_bf16 v[126:129], v[130:133], v[192:195], v[126:129]
	v_mfma_f32_16x16x32_bf16 v[122:125], v[158:161], v[192:195], v[122:125]
	v_mfma_f32_16x16x32_bf16 v[118:121], v[130:133], v[200:203], v[118:121]
	v_mfma_f32_16x16x32_bf16 v[110:113], v[158:161], v[200:203], v[110:113]
	v_mfma_f32_16x16x32_bf16 v[102:105], v[130:133], v[208:211], v[102:105]
	v_mfma_f32_16x16x32_bf16 v[94:97], v[158:161], v[208:211], v[94:97]
	v_mfma_f32_16x16x32_bf16 v[86:89], v[130:133], v[216:219], v[86:89]
	v_mfma_f32_16x16x32_bf16 v[78:81], v[158:161], v[216:219], v[78:81]
	v_mfma_f32_16x16x32_bf16 v[126:129], v[134:137], v[196:199], v[126:129]
	v_mfma_f32_16x16x32_bf16 v[122:125], v[168:171], v[196:199], v[122:125]
	v_mfma_f32_16x16x32_bf16 v[118:121], v[134:137], v[204:207], v[118:121]
	v_mfma_f32_16x16x32_bf16 v[110:113], v[168:171], v[204:207], v[110:113]
	v_mfma_f32_16x16x32_bf16 v[102:105], v[134:137], v[212:215], v[102:105]
	v_mfma_f32_16x16x32_bf16 v[94:97], v[168:171], v[212:215], v[94:97]
	v_mfma_f32_16x16x32_bf16 v[86:89], v[134:137], v[220:223], v[86:89]
	v_mfma_f32_16x16x32_bf16 v[78:81], v[168:171], v[220:223], v[78:81]
	s_setprio 0
	s_setprio 1
	v_mfma_f32_16x16x32_bf16 v[114:117], v[176:179], v[192:195], v[114:117]
	v_mfma_f32_16x16x32_bf16 v[106:109], v[184:187], v[192:195], v[106:109]
	v_mfma_f32_16x16x32_bf16 v[98:101], v[176:179], v[200:203], v[98:101]
	v_mfma_f32_16x16x32_bf16 v[90:93], v[184:187], v[200:203], v[90:93]
	v_mfma_f32_16x16x32_bf16 v[82:85], v[176:179], v[208:211], v[82:85]
	v_mfma_f32_16x16x32_bf16 v[74:77], v[184:187], v[208:211], v[74:77]
	v_mfma_f32_16x16x32_bf16 v[70:73], v[176:179], v[216:219], v[70:73]
	v_mfma_f32_16x16x32_bf16 v[66:69], v[184:187], v[216:219], v[66:69]
	v_mfma_f32_16x16x32_bf16 v[114:117], v[180:183], v[196:199], v[114:117]
	v_mfma_f32_16x16x32_bf16 v[106:109], v[188:191], v[196:199], v[106:109]
	v_mfma_f32_16x16x32_bf16 v[98:101], v[180:183], v[204:207], v[98:101]
	v_mfma_f32_16x16x32_bf16 v[90:93], v[188:191], v[204:207], v[90:93]
	v_mfma_f32_16x16x32_bf16 v[82:85], v[180:183], v[212:215], v[82:85]
	v_mfma_f32_16x16x32_bf16 v[74:77], v[188:191], v[212:215], v[74:77]
	v_mfma_f32_16x16x32_bf16 v[70:73], v[180:183], v[220:223], v[70:73]
	v_mfma_f32_16x16x32_bf16 v[66:69], v[188:191], v[220:223], v[66:69]
	s_setprio 0
	s_barrier
	s_add_i32 s2, s52, s36
	v_lshl_add_u64 v[172:173], v[172:173], 0, s[14:15]
	s_mov_b32 m0, s2
	ds_read_b128 v[192:195], v166 offset:49152
	ds_read_b128 v[196:199], v166 offset:50176
	ds_read_b128 v[200:203], v166 offset:51200
	ds_read_b128 v[204:207], v166 offset:52224
	ds_read_b128 v[208:211], v166 offset:53248
	ds_read_b128 v[212:215], v166 offset:54272
	ds_read_b128 v[216:219], v166 offset:55296
	ds_read_b128 v[220:223], v166 offset:56320
	global_load_lds_dwordx4 v[172:173], off
	s_add_i32 m0, s2, 0x2000
	s_add_u32 s0, s0, 0x80080
	v_lshl_add_u64 v[172:173], v[224:225], 0, s[14:15]
	s_addc_u32 s1, s1, 0
	s_add_i32 s2, s53, s36
	global_load_lds_dwordx4 v[172:173], off
	v_lshl_add_u64 v[172:173], s[0:1], 0, v[144:145]
	s_mov_b32 m0, s2
	s_nop 0
	global_load_lds_dwordx4 v[172:173], off
	v_lshl_add_u64 v[172:173], s[0:1], 0, v[148:149]
	s_add_i32 m0, s2, 0x2000
	s_nop 0
	global_load_lds_dwordx4 v[172:173], off
	v_lshl_add_u64 v[172:173], v[226:227], 0, s[14:15]
	s_mov_b32 m0, s41
	s_nop 0
	global_load_lds_dwordx4 v[172:173], off
	v_lshl_add_u64 v[172:173], v[228:229], 0, s[14:15]
	s_mov_b32 m0, s42
	s_nop 0
	global_load_lds_dwordx4 v[172:173], off
	s_waitcnt vmcnt(8)
	s_waitcnt lgkmcnt(0)
	s_barrier
	s_setprio 1
	s_waitcnt lgkmcnt(0)
	v_mfma_f32_16x16x32_bf16 v[62:65], v[130:133], v[192:195], v[62:65]
	v_mfma_f32_16x16x32_bf16 v[58:61], v[158:161], v[192:195], v[58:61]
	v_mfma_f32_16x16x32_bf16 v[46:49], v[130:133], v[200:203], v[46:49]
	v_mfma_f32_16x16x32_bf16 v[42:45], v[158:161], v[200:203], v[42:45]
	v_mfma_f32_16x16x32_bf16 v[30:33], v[130:133], v[208:211], v[30:33]
	v_mfma_f32_16x16x32_bf16 v[26:29], v[158:161], v[208:211], v[26:29]
	v_mfma_f32_16x16x32_bf16 v[14:17], v[130:133], v[216:219], v[14:17]
	v_mfma_f32_16x16x32_bf16 v[10:13], v[158:161], v[216:219], v[10:13]
	v_mfma_f32_16x16x32_bf16 v[62:65], v[134:137], v[196:199], v[62:65]
	v_mfma_f32_16x16x32_bf16 v[58:61], v[168:171], v[196:199], v[58:61]
	v_mfma_f32_16x16x32_bf16 v[46:49], v[134:137], v[204:207], v[46:49]
	v_mfma_f32_16x16x32_bf16 v[42:45], v[168:171], v[204:207], v[42:45]
	v_mfma_f32_16x16x32_bf16 v[30:33], v[134:137], v[212:215], v[30:33]
	v_mfma_f32_16x16x32_bf16 v[26:29], v[168:171], v[212:215], v[26:29]
	v_mfma_f32_16x16x32_bf16 v[14:17], v[134:137], v[220:223], v[14:17]
	v_mfma_f32_16x16x32_bf16 v[10:13], v[168:171], v[220:223], v[10:13]
	s_setprio 0
	s_setprio 1
	v_mfma_f32_16x16x32_bf16 v[54:57], v[176:179], v[192:195], v[54:57]
	v_mfma_f32_16x16x32_bf16 v[50:53], v[184:187], v[192:195], v[50:53]
	v_mfma_f32_16x16x32_bf16 v[38:41], v[176:179], v[200:203], v[38:41]
	v_mfma_f32_16x16x32_bf16 v[34:37], v[184:187], v[200:203], v[34:37]
	v_mfma_f32_16x16x32_bf16 v[22:25], v[176:179], v[208:211], v[22:25]
	v_mfma_f32_16x16x32_bf16 v[18:21], v[184:187], v[208:211], v[18:21]
	v_mfma_f32_16x16x32_bf16 v[6:9], v[176:179], v[216:219], v[6:9]
	v_mfma_f32_16x16x32_bf16 v[2:5], v[184:187], v[216:219], v[2:5]
	v_mfma_f32_16x16x32_bf16 v[54:57], v[180:183], v[196:199], v[54:57]
	v_mfma_f32_16x16x32_bf16 v[50:53], v[188:191], v[196:199], v[50:53]
	v_mfma_f32_16x16x32_bf16 v[38:41], v[180:183], v[204:207], v[38:41]
	v_mfma_f32_16x16x32_bf16 v[34:37], v[188:191], v[204:207], v[34:37]
	v_mfma_f32_16x16x32_bf16 v[22:25], v[180:183], v[212:215], v[22:25]
	v_mfma_f32_16x16x32_bf16 v[18:21], v[188:191], v[212:215], v[18:21]
	v_mfma_f32_16x16x32_bf16 v[6:9], v[180:183], v[220:223], v[6:9]
	v_mfma_f32_16x16x32_bf16 v[2:5], v[188:191], v[220:223], v[2:5]
	s_setprio 0
	s_add_i32 s51, s51, 2
	s_add_u32 s28, s28, 0x100
	s_addc_u32 s29, s29, 0
	s_add_u32 s49, s49, 0x100
	s_addc_u32 s50, s50, 0
	s_cmp_gt_u32 s51, 29
	s_barrier
	s_cbranch_scc0 .LBB0_1261
	s_and_b64 vcc, exec, s[16:17]
	s_cbranch_vccz .LBB0_1264
	s_barrier

.LBB0_1346:
	ds_read_b128 v[150:153], v154
	ds_read_b128 v[158:161], v154 offset:1024
	ds_read_b128 v[162:165], v154 offset:2048
	ds_read_b128 v[166:169], v154 offset:3072
	ds_read_b128 v[170:173], v155
	ds_read_b128 v[176:179], v155 offset:1024
	ds_read_b128 v[180:183], v155 offset:2048
	ds_read_b128 v[184:187], v155 offset:3072
	s_add_u32 s0, s30, 0xfff80080
	s_addc_u32 s1, s31, -1
	s_cmp_eq_u32 s51, 28
	s_cselect_b32 s3, s25, s1
	s_cselect_b32 s2, s47, s0
	s_cselect_b32 s1, s23, s50
	s_cselect_b32 s0, s48, s49
	v_lshl_add_u64 v[220:221], s[30:31], 0, v[142:143]
	s_add_i32 m0, s5, 0xc000
	ds_read_b128 v[188:191], v156
	ds_read_b128 v[192:195], v156 offset:1024
	ds_read_b128 v[196:199], v156 offset:2048
	ds_read_b128 v[200:203], v156 offset:3072
	ds_read_b128 v[204:207], v156 offset:4096
	ds_read_b128 v[208:211], v156 offset:5120
	ds_read_b128 v[212:215], v156 offset:6144
	ds_read_b128 v[216:219], v156 offset:7168
	global_load_lds_dwordx4 v[220:221], off
	v_lshl_add_u64 v[220:221], s[30:31], 0, v[144:145]
	s_add_i32 m0, s5, 0xe000
	s_nop 0
	global_load_lds_dwordx4 v[220:221], off
	s_waitcnt vmcnt(8)
	s_waitcnt lgkmcnt(0)
	s_barrier
	s_setprio 1
	s_waitcnt lgkmcnt(0)
	v_mfma_f32_16x16x32_bf16 v[126:129], v[150:153], v[188:191], v[126:129]
	v_mfma_f32_16x16x32_bf16 v[122:125], v[162:165], v[188:191], v[122:125]
	v_mfma_f32_16x16x32_bf16 v[110:113], v[150:153], v[196:199], v[110:113]
	v_mfma_f32_16x16x32_bf16 v[106:109], v[162:165], v[196:199], v[106:109]
	v_mfma_f32_16x16x32_bf16 v[94:97], v[150:153], v[204:207], v[94:97]
	v_mfma_f32_16x16x32_bf16 v[90:93], v[162:165], v[204:207], v[90:93]
	v_mfma_f32_16x16x32_bf16 v[78:81], v[150:153], v[212:215], v[78:81]
	v_mfma_f32_16x16x32_bf16 v[74:77], v[162:165], v[212:215], v[74:77]
	v_mfma_f32_16x16x32_bf16 v[126:129], v[158:161], v[192:195], v[126:129]
	v_mfma_f32_16x16x32_bf16 v[122:125], v[166:169], v[192:195], v[122:125]
	v_mfma_f32_16x16x32_bf16 v[110:113], v[158:161], v[200:203], v[110:113]
	v_mfma_f32_16x16x32_bf16 v[106:109], v[166:169], v[200:203], v[106:109]
	v_mfma_f32_16x16x32_bf16 v[94:97], v[158:161], v[208:211], v[94:97]
	v_mfma_f32_16x16x32_bf16 v[90:93], v[166:169], v[208:211], v[90:93]
	v_mfma_f32_16x16x32_bf16 v[78:81], v[158:161], v[216:219], v[78:81]
	v_mfma_f32_16x16x32_bf16 v[74:77], v[166:169], v[216:219], v[74:77]
	s_setprio 0
	s_setprio 1
	v_mfma_f32_16x16x32_bf16 v[118:121], v[170:173], v[188:191], v[118:121]
	v_mfma_f32_16x16x32_bf16 v[114:117], v[180:183], v[188:191], v[114:117]
	v_mfma_f32_16x16x32_bf16 v[102:105], v[170:173], v[196:199], v[102:105]
	v_mfma_f32_16x16x32_bf16 v[98:101], v[180:183], v[196:199], v[98:101]
	v_mfma_f32_16x16x32_bf16 v[86:89], v[170:173], v[204:207], v[86:89]
	v_mfma_f32_16x16x32_bf16 v[82:85], v[180:183], v[204:207], v[82:85]
	v_mfma_f32_16x16x32_bf16 v[70:73], v[170:173], v[212:215], v[70:73]
	v_mfma_f32_16x16x32_bf16 v[66:69], v[180:183], v[212:215], v[66:69]
	v_mfma_f32_16x16x32_bf16 v[118:121], v[176:179], v[192:195], v[118:121]
	v_mfma_f32_16x16x32_bf16 v[114:117], v[184:187], v[192:195], v[114:117]
	v_mfma_f32_16x16x32_bf16 v[102:105], v[176:179], v[200:203], v[102:105]
	v_mfma_f32_16x16x32_bf16 v[98:101], v[184:187], v[200:203], v[98:101]
	v_mfma_f32_16x16x32_bf16 v[86:89], v[176:179], v[208:211], v[86:89]
	v_mfma_f32_16x16x32_bf16 v[82:85], v[184:187], v[208:211], v[82:85]
	v_mfma_f32_16x16x32_bf16 v[70:73], v[176:179], v[216:219], v[70:73]
	v_mfma_f32_16x16x32_bf16 v[66:69], v[184:187], v[216:219], v[66:69]
	s_setprio 0
	s_barrier
	s_add_i32 s52, s44, s36
	v_lshl_add_u64 v[220:221], s[0:1], 0, v[134:135]
	s_mov_b32 m0, s52
	ds_read_b128 v[188:191], v156 offset:16384
	ds_read_b128 v[192:195], v156 offset:17408
	ds_read_b128 v[196:199], v156 offset:18432
	ds_read_b128 v[200:203], v156 offset:19456
	ds_read_b128 v[204:207], v156 offset:20480
	ds_read_b128 v[208:211], v156 offset:21504
	ds_read_b128 v[212:215], v156 offset:22528
	ds_read_b128 v[216:219], v156 offset:23552
	global_load_lds_dwordx4 v[220:221], off
	s_add_i32 m0, s52, 0x2000
	s_add_u32 s52, s0, 0x80000
	v_lshl_add_u64 v[222:223], s[0:1], 0, v[140:141]
	s_addc_u32 s53, s1, 0
	s_add_i32 s54, s45, s36
	global_load_lds_dwordx4 v[222:223], off
	v_lshl_add_u64 v[224:225], s[52:53], 0, v[134:135]
	s_mov_b32 m0, s54
	v_lshl_add_u64 v[226:227], s[2:3], 0, v[136:137]
	global_load_lds_dwordx4 v[224:225], off
	v_lshl_add_u64 v[224:225], s[52:53], 0, v[140:141]
	s_add_i32 m0, s54, 0x2000
	s_nop 0
	global_load_lds_dwordx4 v[224:225], off
	v_lshl_add_u64 v[224:225], s[2:3], 0, v[132:133]
	s_mov_b32 m0, s5
	s_nop 0
	global_load_lds_dwordx4 v[224:225], off
	s_mov_b32 m0, s37
	s_nop 0
	global_load_lds_dwordx4 v[226:227], off
	s_waitcnt vmcnt(8)
	s_waitcnt lgkmcnt(0)
	s_barrier
	s_setprio 1
	s_waitcnt lgkmcnt(0)
	v_mfma_f32_16x16x32_bf16 v[62:65], v[150:153], v[188:191], v[62:65]
	v_mfma_f32_16x16x32_bf16 v[58:61], v[162:165], v[188:191], v[58:61]
	v_mfma_f32_16x16x32_bf16 v[46:49], v[150:153], v[196:199], v[46:49]
	v_mfma_f32_16x16x32_bf16 v[42:45], v[162:165], v[196:199], v[42:45]
	v_mfma_f32_16x16x32_bf16 v[30:33], v[150:153], v[204:207], v[30:33]
	v_mfma_f32_16x16x32_bf16 v[26:29], v[162:165], v[204:207], v[26:29]
	v_mfma_f32_16x16x32_bf16 v[14:17], v[150:153], v[212:215], v[14:17]
	v_mfma_f32_16x16x32_bf16 v[10:13], v[162:165], v[212:215], v[10:13]
	v_mfma_f32_16x16x32_bf16 v[62:65], v[158:161], v[192:195], v[62:65]
	v_mfma_f32_16x16x32_bf16 v[58:61], v[166:169], v[192:195], v[58:61]
	v_mfma_f32_16x16x32_bf16 v[46:49], v[158:161], v[200:203], v[46:49]
	v_mfma_f32_16x16x32_bf16 v[42:45], v[166:169], v[200:203], v[42:45]
	v_mfma_f32_16x16x32_bf16 v[30:33], v[158:161], v[208:211], v[30:33]
	v_mfma_f32_16x16x32_bf16 v[26:29], v[166:169], v[208:211], v[26:29]
	v_mfma_f32_16x16x32_bf16 v[14:17], v[158:161], v[216:219], v[14:17]
	v_mfma_f32_16x16x32_bf16 v[10:13], v[166:169], v[216:219], v[10:13]
	s_setprio 0
	s_setprio 1
	v_mfma_f32_16x16x32_bf16 v[54:57], v[170:173], v[188:191], v[54:57]
	v_mfma_f32_16x16x32_bf16 v[50:53], v[180:183], v[188:191], v[50:53]
	v_mfma_f32_16x16x32_bf16 v[38:41], v[170:173], v[196:199], v[38:41]
	v_mfma_f32_16x16x32_bf16 v[34:37], v[180:183], v[196:199], v[34:37]
	v_mfma_f32_16x16x32_bf16 v[22:25], v[170:173], v[204:207], v[22:25]
	v_mfma_f32_16x16x32_bf16 v[18:21], v[180:183], v[204:207], v[18:21]
	v_mfma_f32_16x16x32_bf16 v[6:9], v[170:173], v[212:215], v[6:9]
	v_mfma_f32_16x16x32_bf16 v[2:5], v[180:183], v[212:215], v[2:5]
	v_mfma_f32_16x16x32_bf16 v[54:57], v[176:179], v[192:195], v[54:57]
	v_mfma_f32_16x16x32_bf16 v[50:53], v[184:187], v[192:195], v[50:53]
	v_mfma_f32_16x16x32_bf16 v[38:41], v[176:179], v[200:203], v[38:41]
	v_mfma_f32_16x16x32_bf16 v[34:37], v[184:187], v[200:203], v[34:37]
	v_mfma_f32_16x16x32_bf16 v[22:25], v[176:179], v[208:211], v[22:25]
	v_mfma_f32_16x16x32_bf16 v[18:21], v[184:187], v[208:211], v[18:21]
	v_mfma_f32_16x16x32_bf16 v[6:9], v[176:179], v[216:219], v[6:9]
	v_mfma_f32_16x16x32_bf16 v[2:5], v[184:187], v[216:219], v[2:5]
	s_setprio 0
	s_barrier
	s_add_i32 s52, 0, 0x18000
	v_add_u32_e32 v157, s52, v131
	s_add_i32 s53, 0, 0x1c000
	ds_read_b128 v[150:153], v157
	ds_read_b128 v[158:161], v157 offset:1024
	ds_read_b128 v[162:165], v157 offset:2048
	ds_read_b128 v[166:169], v157 offset:3072
	v_add_u32_e32 v157, s53, v131
	ds_read_b128 v[170:173], v157
	ds_read_b128 v[176:179], v157 offset:1024
	ds_read_b128 v[180:183], v157 offset:2048
	ds_read_b128 v[184:187], v157 offset:3072
	s_add_u32 s2, s2, 0x80000
	s_addc_u32 s3, s3, 0
	s_mov_b32 m0, s38
	v_lshl_add_u64 v[228:229], s[2:3], 0, v[132:133]
	ds_read_b128 v[188:191], v156 offset:32768
	ds_read_b128 v[192:195], v156 offset:33792
	ds_read_b128 v[196:199], v156 offset:34816
	ds_read_b128 v[200:203], v156 offset:35840
	ds_read_b128 v[204:207], v156 offset:36864
	ds_read_b128 v[208:211], v156 offset:37888
	ds_read_b128 v[212:215], v156 offset:38912
	ds_read_b128 v[216:219], v156 offset:39936
	global_load_lds_dwordx4 v[228:229], off
	v_lshl_add_u64 v[228:229], s[2:3], 0, v[136:137]
	s_mov_b32 m0, s39
	s_nop 0
	global_load_lds_dwordx4 v[228:229], off
	s_waitcnt vmcnt(8)
	s_waitcnt lgkmcnt(0)
	s_barrier
	s_setprio 1
	s_waitcnt lgkmcnt(0)
	v_mfma_f32_16x16x32_bf16 v[126:129], v[150:153], v[188:191], v[126:129]
	v_mfma_f32_16x16x32_bf16 v[122:125], v[162:165], v[188:191], v[122:125]
	v_mfma_f32_16x16x32_bf16 v[110:113], v[150:153], v[196:199], v[110:113]
	v_mfma_f32_16x16x32_bf16 v[106:109], v[162:165], v[196:199], v[106:109]
	v_mfma_f32_16x16x32_bf16 v[94:97], v[150:153], v[204:207], v[94:97]
	v_mfma_f32_16x16x32_bf16 v[90:93], v[162:165], v[204:207], v[90:93]
	v_mfma_f32_16x16x32_bf16 v[78:81], v[150:153], v[212:215], v[78:81]
	v_mfma_f32_16x16x32_bf16 v[74:77], v[162:165], v[212:215], v[74:77]
	v_mfma_f32_16x16x32_bf16 v[126:129], v[158:161], v[192:195], v[126:129]
	v_mfma_f32_16x16x32_bf16 v[122:125], v[166:169], v[192:195], v[122:125]
	v_mfma_f32_16x16x32_bf16 v[110:113], v[158:161], v[200:203], v[110:113]
	v_mfma_f32_16x16x32_bf16 v[106:109], v[166:169], v[200:203], v[106:109]
	v_mfma_f32_16x16x32_bf16 v[94:97], v[158:161], v[208:211], v[94:97]
	v_mfma_f32_16x16x32_bf16 v[90:93], v[166:169], v[208:211], v[90:93]
	v_mfma_f32_16x16x32_bf16 v[78:81], v[158:161], v[216:219], v[78:81]
	v_mfma_f32_16x16x32_bf16 v[74:77], v[166:169], v[216:219], v[74:77]
	s_setprio 0
	s_setprio 1
	v_mfma_f32_16x16x32_bf16 v[118:121], v[170:173], v[188:191], v[118:121]
	v_mfma_f32_16x16x32_bf16 v[114:117], v[180:183], v[188:191], v[114:117]
	v_mfma_f32_16x16x32_bf16 v[102:105], v[170:173], v[196:199], v[102:105]
	v_mfma_f32_16x16x32_bf16 v[98:101], v[180:183], v[196:199], v[98:101]
	v_mfma_f32_16x16x32_bf16 v[86:89], v[170:173], v[204:207], v[86:89]
	v_mfma_f32_16x16x32_bf16 v[82:85], v[180:183], v[204:207], v[82:85]
	v_mfma_f32_16x16x32_bf16 v[70:73], v[170:173], v[212:215], v[70:73]
	v_mfma_f32_16x16x32_bf16 v[66:69], v[180:183], v[212:215], v[66:69]
	v_mfma_f32_16x16x32_bf16 v[118:121], v[176:179], v[192:195], v[118:121]
	v_mfma_f32_16x16x32_bf16 v[114:117], v[184:187], v[192:195], v[114:117]
	v_mfma_f32_16x16x32_bf16 v[102:105], v[176:179], v[200:203], v[102:105]
	v_mfma_f32_16x16x32_bf16 v[98:101], v[184:187], v[200:203], v[98:101]
	v_mfma_f32_16x16x32_bf16 v[86:89], v[176:179], v[208:211], v[86:89]
	v_mfma_f32_16x16x32_bf16 v[82:85], v[184:187], v[208:211], v[82:85]
	v_mfma_f32_16x16x32_bf16 v[70:73], v[176:179], v[216:219], v[70:73]
	v_mfma_f32_16x16x32_bf16 v[66:69], v[184:187], v[216:219], v[66:69]
	s_setprio 0
	s_barrier
	s_add_i32 s2, s52, s36
	v_lshl_add_u64 v[220:221], v[220:221], 0, s[18:19]
	s_mov_b32 m0, s2
	ds_read_b128 v[188:191], v156 offset:49152
	ds_read_b128 v[192:195], v156 offset:50176
	ds_read_b128 v[196:199], v156 offset:51200
	ds_read_b128 v[200:203], v156 offset:52224
	ds_read_b128 v[204:207], v156 offset:53248
	ds_read_b128 v[208:211], v156 offset:54272
	ds_read_b128 v[212:215], v156 offset:55296
	ds_read_b128 v[216:219], v156 offset:56320
	global_load_lds_dwordx4 v[220:221], off
	s_add_i32 m0, s2, 0x2000
	s_add_u32 s0, s0, 0x80080
	v_lshl_add_u64 v[220:221], v[222:223], 0, s[18:19]
	s_addc_u32 s1, s1, 0
	s_add_i32 s2, s53, s36
	global_load_lds_dwordx4 v[220:221], off
	v_lshl_add_u64 v[220:221], s[0:1], 0, v[134:135]
	s_mov_b32 m0, s2
	s_nop 0
	global_load_lds_dwordx4 v[220:221], off
	v_lshl_add_u64 v[220:221], s[0:1], 0, v[140:141]
	s_add_i32 m0, s2, 0x2000
	s_nop 0
	global_load_lds_dwordx4 v[220:221], off
	v_lshl_add_u64 v[220:221], v[224:225], 0, s[18:19]
	s_mov_b32 m0, s41
	s_nop 0
	global_load_lds_dwordx4 v[220:221], off
	v_lshl_add_u64 v[220:221], v[226:227], 0, s[18:19]
	s_mov_b32 m0, s42
	s_nop 0
	global_load_lds_dwordx4 v[220:221], off
	s_waitcnt vmcnt(8)
	s_waitcnt lgkmcnt(0)
	s_barrier
	s_setprio 1
	s_waitcnt lgkmcnt(0)
	v_mfma_f32_16x16x32_bf16 v[62:65], v[150:153], v[188:191], v[62:65]
	v_mfma_f32_16x16x32_bf16 v[58:61], v[162:165], v[188:191], v[58:61]
	v_mfma_f32_16x16x32_bf16 v[46:49], v[150:153], v[196:199], v[46:49]
	v_mfma_f32_16x16x32_bf16 v[42:45], v[162:165], v[196:199], v[42:45]
	v_mfma_f32_16x16x32_bf16 v[30:33], v[150:153], v[204:207], v[30:33]
	v_mfma_f32_16x16x32_bf16 v[26:29], v[162:165], v[204:207], v[26:29]
	v_mfma_f32_16x16x32_bf16 v[14:17], v[150:153], v[212:215], v[14:17]
	v_mfma_f32_16x16x32_bf16 v[10:13], v[162:165], v[212:215], v[10:13]
	v_mfma_f32_16x16x32_bf16 v[62:65], v[158:161], v[192:195], v[62:65]
	v_mfma_f32_16x16x32_bf16 v[58:61], v[166:169], v[192:195], v[58:61]
	v_mfma_f32_16x16x32_bf16 v[46:49], v[158:161], v[200:203], v[46:49]
	v_mfma_f32_16x16x32_bf16 v[42:45], v[166:169], v[200:203], v[42:45]
	v_mfma_f32_16x16x32_bf16 v[30:33], v[158:161], v[208:211], v[30:33]
	v_mfma_f32_16x16x32_bf16 v[26:29], v[166:169], v[208:211], v[26:29]
	v_mfma_f32_16x16x32_bf16 v[14:17], v[158:161], v[216:219], v[14:17]
	v_mfma_f32_16x16x32_bf16 v[10:13], v[166:169], v[216:219], v[10:13]
	s_setprio 0
	s_setprio 1
	v_mfma_f32_16x16x32_bf16 v[54:57], v[170:173], v[188:191], v[54:57]
	v_mfma_f32_16x16x32_bf16 v[50:53], v[180:183], v[188:191], v[50:53]
	v_mfma_f32_16x16x32_bf16 v[38:41], v[170:173], v[196:199], v[38:41]
	v_mfma_f32_16x16x32_bf16 v[34:37], v[180:183], v[196:199], v[34:37]
	v_mfma_f32_16x16x32_bf16 v[22:25], v[170:173], v[204:207], v[22:25]
	v_mfma_f32_16x16x32_bf16 v[18:21], v[180:183], v[204:207], v[18:21]
	v_mfma_f32_16x16x32_bf16 v[6:9], v[170:173], v[212:215], v[6:9]
	v_mfma_f32_16x16x32_bf16 v[2:5], v[180:183], v[212:215], v[2:5]
	v_mfma_f32_16x16x32_bf16 v[54:57], v[176:179], v[192:195], v[54:57]
	v_mfma_f32_16x16x32_bf16 v[50:53], v[184:187], v[192:195], v[50:53]
	v_mfma_f32_16x16x32_bf16 v[38:41], v[176:179], v[200:203], v[38:41]
	v_mfma_f32_16x16x32_bf16 v[34:37], v[184:187], v[200:203], v[34:37]
	v_mfma_f32_16x16x32_bf16 v[22:25], v[176:179], v[208:211], v[22:25]
	v_mfma_f32_16x16x32_bf16 v[18:21], v[184:187], v[208:211], v[18:21]
	v_mfma_f32_16x16x32_bf16 v[6:9], v[176:179], v[216:219], v[6:9]
	v_mfma_f32_16x16x32_bf16 v[2:5], v[184:187], v[216:219], v[2:5]
	s_setprio 0
	s_add_i32 s51, s51, 2
	s_add_u32 s30, s30, 0x100
	s_addc_u32 s31, s31, 0
	s_add_u32 s49, s49, 0x100
	s_addc_u32 s50, s50, 0
	s_cmp_gt_u32 s51, 29
	s_barrier
	s_cbranch_scc0 .LBB0_1346
	s_and_b64 vcc, exec, s[20:21]
	s_cbranch_vccz .LBB0_1349
	s_barrier
